# conv / SSM items dealt to the XCD owning their tokens: seams 3,4,5 XCD-local as well (11 local seams, 4 rendezvous-only, 3 full)
# speedup vs baseline: 1.0374x; 1.0026x over previous
; #define LAS __attribute__((address_space(3)))
; #define CONV_LOAD(dst, it_) do { const int t0_ = (it_) * 16 + th * 8, tb_ = t0_ & (SEQ - 1); \
;         _Pragma("unroll") for (int r = 0; r < 38; ++r) { const int pos = tb_ - 30 + r; dst[r] = *(const unsigned*)(VC + (size_t)(t0_ - tb_ + (pos < 0 ? 0 : pos)) * CONVC + 2 * cp); } } while (0)
; __device__ __forceinline__ void conv_phase(LAS unsigned char* lds, const bf16_t* VC, const float* cw, const float* cb, const float* lng, const float* lnb, bf16_t* CAT, int tid, int lane, int wave) {
;     const int cp = tid & 255, th = tid >> 8;
;     f32x2v wk[TAPS];
; #pragma unroll
;     for (int k = 0; k < TAPS; ++k) wk[k] = *(const f32x2v*)(cw + k * CONVC + 2 * cp);
;     const f32x2v bias = *(const f32x2v*)(cb + 2 * cp);
;     LAS float* ybuf = (LAS float*)lds;
;     unsigned vn[38];
;     ...
;     if ((int)blockIdx.x < T / 16) CONV_LOAD(vn, (int)blockIdx.x);
;     for (int it = blockIdx.x; it < T / 16; it += gridDim.x) {
;         const int t0 = it * 16 + th * 8, tb = t0 & (SEQ - 1);
;         f32x2v av[8];
; #pragma unroll
;         for (int t = 0; t < 8; ++t) av[t] = bias;
;         unsigned vv[38];
; #pragma unroll
;         for (int r = 0; r < 38; ++r) vv[r] = vn[r];
;         if (it + (int)gridDim.x < T / 16) CONV_LOAD(vn, it + (int)gridDim.x);
.LBB0_479:
	s_cmp_lt_i32 s30, 5
	s_cselect_b64 s[4:5], -1, 0
	s_add_u32 s42, s28, 0x12800000
	s_addc_u32 s43, s29, 0
	s_add_u32 s6, s28, 0x200000
	s_addc_u32 s7, s29, 0
	s_and_b64 s[8:9], s[4:5], s[0:1]
	s_andn2_b64 vcc, exec, s[8:9]
	s_cbranch_vccnz .LBB0_490
	s_cmpk_gt_i32 s2, 0x7ff
	s_cbranch_scc1 .LBB0_485
	v_lshlrev_b32_e32 v0, 1, v197
	v_and_b32_e32 v6, 0x1fe, v0
	v_lshlrev_b32_e32 v24, 2, v6
	v_mov_b32_e32 v25, 0
	s_waitcnt lgkmcnt(0)
	v_lshl_add_u64 v[0:1], s[82:83], 0, v[24:25]
	v_add_co_u32_e32 v2, vcc, 0x1000, v0
	v_lshrrev_b32_e32 v99, 8, v197
	s_nop 0
	v_addc_co_u32_e32 v3, vcc, 0, v1, vcc
	v_add_co_u32_e32 v4, vcc, 0x2000, v0
	s_lshl_b32 s3, s2, 4
	s_nop 0
	v_addc_co_u32_e32 v5, vcc, 0, v1, vcc
	global_load_dwordx2 v[26:27], v[2:3], off
	global_load_dwordx2 v[28:29], v[2:3], off offset:2048
	global_load_dwordx2 v[30:31], v[4:5], off
	global_load_dwordx2 v[32:33], v[4:5], off offset:2048
	v_add_co_u32_e32 v2, vcc, 0x3000, v0
	v_lshlrev_b32_e32 v98, 3, v99
	s_nop 0
	v_addc_co_u32_e32 v3, vcc, 0, v1, vcc
	v_add_co_u32_e32 v4, vcc, 0x4000, v0
	v_readlane_b32 s48, v249, 2
	s_nop 0
	v_addc_co_u32_e32 v5, vcc, 0, v1, vcc
	global_load_dwordx2 v[34:35], v[2:3], off
	global_load_dwordx2 v[36:37], v[2:3], off offset:2048
	global_load_dwordx2 v[38:39], v[4:5], off
	global_load_dwordx2 v[40:41], v[4:5], off offset:2048
	v_add_co_u32_e32 v2, vcc, 0x5000, v0
	v_readlane_b32 s49, v249, 3
	s_nop 0
	v_addc_co_u32_e32 v3, vcc, 0, v1, vcc
	v_add_co_u32_e32 v4, vcc, 0x6000, v0
	v_readlane_b32 s50, v249, 4
	s_nop 0
	v_addc_co_u32_e32 v5, vcc, 0, v1, vcc
	global_load_dwordx2 v[42:43], v[2:3], off
	global_load_dwordx2 v[44:45], v[2:3], off offset:2048
	global_load_dwordx2 v[46:47], v[4:5], off
	global_load_dwordx2 v[48:49], v[4:5], off offset:2048
	v_add_co_u32_e32 v2, vcc, 0x7000, v0
	v_readlane_b32 s51, v249, 5
	s_nop 0
	v_addc_co_u32_e32 v3, vcc, 0, v1, vcc
	v_add_co_u32_e32 v4, vcc, 0x8000, v0
	v_readlane_b32 s52, v249, 6
	s_nop 0
	v_addc_co_u32_e32 v5, vcc, 0, v1, vcc
	global_load_dwordx2 v[50:51], v[2:3], off
	global_load_dwordx2 v[52:53], v[2:3], off offset:2048
	global_load_dwordx2 v[54:55], v[4:5], off
	global_load_dwordx2 v[56:57], v[4:5], off offset:2048
	v_add_co_u32_e32 v2, vcc, 0x9000, v0
	v_readlane_b32 s53, v249, 7
	s_nop 0
	v_addc_co_u32_e32 v3, vcc, 0, v1, vcc
	v_add_co_u32_e32 v4, vcc, 0xa000, v0
	s_mov_b64 s[12:13], s[48:49]
	s_nop 0
	v_addc_co_u32_e32 v5, vcc, 0, v1, vcc
	global_load_dwordx2 v[58:59], v[2:3], off
	global_load_dwordx2 v[60:61], v[2:3], off offset:2048
	global_load_dwordx2 v[62:63], v[4:5], off
	global_load_dwordx2 v[64:65], v[4:5], off offset:2048
	v_add_co_u32_e32 v2, vcc, 0xb000, v0
	s_mov_b64 s[14:15], s[50:51]
	s_nop 0
	v_addc_co_u32_e32 v3, vcc, 0, v1, vcc
	v_add_co_u32_e32 v4, vcc, 0xc000, v0
	s_mov_b64 s[16:17], s[52:53]
	s_nop 0
	v_addc_co_u32_e32 v5, vcc, 0, v1, vcc
	global_load_dwordx2 v[66:67], v[2:3], off
	global_load_dwordx2 v[68:69], v[2:3], off offset:2048
	global_load_dwordx2 v[70:71], v[4:5], off
	global_load_dwordx2 v[72:73], v[4:5], off offset:2048
	v_add_co_u32_e32 v2, vcc, 0xd000, v0
	v_readlane_b32 s1, v249, 18
	s_nop 0
	v_addc_co_u32_e32 v3, vcc, 0, v1, vcc
	v_add_co_u32_e32 v4, vcc, 0xe000, v0
	s_lshl_b32 s0, s1, 12
	s_nop 0
	v_addc_co_u32_e32 v5, vcc, 0, v1, vcc
	v_add_co_u32_e32 v0, vcc, 0xf000, v0
	global_load_dwordx2 v[74:75], v[2:3], off
	global_load_dwordx2 v[76:77], v[2:3], off offset:2048
	global_load_dwordx2 v[78:79], v[4:5], off
	global_load_dwordx2 v[80:81], v[4:5], off offset:2048
	v_addc_co_u32_e32 v1, vcc, 0, v1, vcc
	global_load_dwordx2 v[82:83], v[0:1], off
	global_load_dwordx2 v[84:85], v24, s[82:83]
	global_load_dwordx2 v[86:87], v24, s[82:83] offset:2048
	s_bfe_u32 s98, s3, 0x30004
	s_lshl_b32 s98, s98, 12
	s_lshr_b32 s99, s3, 7
	s_lshl_b32 s99, s99, 4
	s_or_b32 s98, s98, s99
	v_add_u32_e32 v0, s98, v98
	v_and_b32_e32 v1, 0x7f8, v0
	v_lshlrev_b32_e32 v2, 1, v6
	v_mov_b32_e32 v3, v25
	v_and_b32_e32 v18, 0xfffff800, v0
	v_lshl_add_u64 v[90:91], s[40:41], 0, v[2:3]
	v_sub_u32_e64 v2, v1, 30 clamp
	v_sub_u32_e64 v14, v1, 24 clamp
	v_or_b32_e32 v2, v2, v18
	v_sub_u32_e64 v4, v1, 29 clamp
	v_sub_u32_e64 v6, v1, 28 clamp
	v_sub_u32_e64 v8, v1, 27 clamp
	v_sub_u32_e64 v10, v1, 26 clamp
	v_sub_u32_e64 v12, v1, 25 clamp
	v_or_b32_e32 v14, v14, v18
	v_sub_u32_e64 v16, v1, 23 clamp
	v_ashrrev_i32_e32 v3, 31, v2
	v_or_b32_e32 v4, v4, v18
	v_or_b32_e32 v6, v6, v18
	v_or_b32_e32 v8, v8, v18
	v_or_b32_e32 v10, v10, v18
	v_or_b32_e32 v12, v12, v18
	v_ashrrev_i32_e32 v15, 31, v14
	v_or_b32_e32 v16, v16, v18
	v_lshlrev_b64 v[2:3], 10, v[2:3]
	v_ashrrev_i32_e32 v5, 31, v4
	v_ashrrev_i32_e32 v7, 31, v6
	v_ashrrev_i32_e32 v9, 31, v8
	v_ashrrev_i32_e32 v11, 31, v10
	v_ashrrev_i32_e32 v13, 31, v12
	v_lshlrev_b64 v[14:15], 10, v[14:15]
	v_ashrrev_i32_e32 v17, 31, v16
	v_lshl_add_u64 v[2:3], v[90:91], 0, v[2:3]
	v_lshlrev_b64 v[4:5], 10, v[4:5]
	v_lshlrev_b64 v[6:7], 10, v[6:7]
	v_lshlrev_b64 v[8:9], 10, v[8:9]
	v_lshlrev_b64 v[10:11], 10, v[10:11]
	v_lshlrev_b64 v[12:13], 10, v[12:13]
	v_lshl_add_u64 v[14:15], v[90:91], 0, v[14:15]
	v_lshlrev_b64 v[16:17], 10, v[16:17]
	global_load_dwordx2 v[88:89], v24, s[12:13]
	v_lshl_add_u64 v[4:5], v[90:91], 0, v[4:5]
	v_lshl_add_u64 v[6:7], v[90:91], 0, v[6:7]
	v_lshl_add_u64 v[8:9], v[90:91], 0, v[8:9]
	v_lshl_add_u64 v[10:11], v[90:91], 0, v[10:11]
	v_lshl_add_u64 v[12:13], v[90:91], 0, v[12:13]
	v_lshl_add_u64 v[16:17], v[90:91], 0, v[16:17]
	global_load_dword v159, v[2:3], off
	global_load_dword v158, v[4:5], off
	global_load_dword v156, v[6:7], off
	global_load_dword v155, v[8:9], off
	global_load_dword v152, v[10:11], off
	global_load_dword v149, v[12:13], off
; #define CONV_LOAD(dst, it_) do { const int t0_ = (it_) * 16 + th * 8, tb_ = t0_ & (SEQ - 1); \
;         _Pragma("unroll") for (int r = 0; r < 38; ++r) { const int pos = tb_ - 30 + r; dst[r] = *(const unsigned*)(VC + (size_t)(t0_ - tb_ + (pos < 0 ? 0 : pos)) * CONVC + 2 * cp); } } while (0)
; __device__ __forceinline__ void conv_phase(LAS unsigned char* lds, const bf16_t* VC, const float* cw, const float* cb, const float* lng, const float* lnb, bf16_t* CAT, int tid, int lane, int wave) {
;     ...
;     if ((int)blockIdx.x < T / 16) CONV_LOAD(vn, (int)blockIdx.x);
	global_load_dword v147, v[14:15], off
	global_load_dword v23, v[16:17], off
	v_sub_u32_e64 v14, v1, 16 clamp
	v_or_b32_e32 v14, v14, v18
	v_ashrrev_i32_e32 v15, 31, v14
	v_sub_u32_e64 v2, v1, 22 clamp
	v_sub_u32_e64 v6, v1, 20 clamp
	v_lshlrev_b64 v[14:15], 10, v[14:15]
	v_or_b32_e32 v2, v2, v18
	v_sub_u32_e64 v4, v1, 21 clamp
	v_or_b32_e32 v6, v6, v18
	v_sub_u32_e64 v8, v1, 19 clamp
	v_sub_u32_e64 v10, v1, 18 clamp
	v_sub_u32_e64 v12, v1, 17 clamp
	v_lshl_add_u64 v[16:17], v[90:91], 0, v[14:15]
	v_sub_u32_e64 v14, v1, 15 clamp
	v_ashrrev_i32_e32 v3, 31, v2
	v_or_b32_e32 v4, v4, v18
	v_ashrrev_i32_e32 v7, 31, v6
	v_or_b32_e32 v8, v8, v18
	v_or_b32_e32 v10, v10, v18
	v_or_b32_e32 v12, v12, v18
	v_or_b32_e32 v14, v14, v18
	v_lshlrev_b64 v[2:3], 10, v[2:3]
	v_ashrrev_i32_e32 v5, 31, v4
	v_lshlrev_b64 v[6:7], 10, v[6:7]
	v_ashrrev_i32_e32 v9, 31, v8
	v_ashrrev_i32_e32 v11, 31, v10
	v_ashrrev_i32_e32 v13, 31, v12
	v_ashrrev_i32_e32 v15, 31, v14
	v_lshl_add_u64 v[2:3], v[90:91], 0, v[2:3]
	v_lshlrev_b64 v[4:5], 10, v[4:5]
	v_lshl_add_u64 v[6:7], v[90:91], 0, v[6:7]
	v_lshlrev_b64 v[8:9], 10, v[8:9]
	v_lshlrev_b64 v[10:11], 10, v[10:11]
	v_lshlrev_b64 v[12:13], 10, v[12:13]
	v_lshlrev_b64 v[14:15], 10, v[14:15]
	v_lshl_add_u64 v[4:5], v[90:91], 0, v[4:5]
	v_lshl_add_u64 v[8:9], v[90:91], 0, v[8:9]
	v_lshl_add_u64 v[10:11], v[90:91], 0, v[10:11]
	v_lshl_add_u64 v[12:13], v[90:91], 0, v[12:13]
	v_lshl_add_u64 v[20:21], v[90:91], 0, v[14:15]
	global_load_dword v160, v[2:3], off
	global_load_dword v157, v[4:5], off
	global_load_dword v154, v[6:7], off
	global_load_dword v151, v[8:9], off
	global_load_dword v148, v[10:11], off
	global_load_dword v22, v[12:13], off
	global_load_dword v19, v[16:17], off
	global_load_dword v15, v[20:21], off
	v_sub_u32_e64 v6, v1, 12 clamp
	v_or_b32_e32 v6, v6, v18
	v_ashrrev_i32_e32 v7, 31, v6
	v_lshlrev_b64 v[6:7], 10, v[6:7]
	v_lshl_add_u64 v[8:9], v[90:91], 0, v[6:7]
	v_sub_u32_e64 v6, v1, 11 clamp
	v_or_b32_e32 v6, v6, v18
	v_ashrrev_i32_e32 v7, 31, v6
	v_lshlrev_b64 v[6:7], 10, v[6:7]
	v_lshl_add_u64 v[12:13], v[90:91], 0, v[6:7]
	v_sub_u32_e64 v6, v1, 10 clamp
	v_or_b32_e32 v6, v6, v18
	v_ashrrev_i32_e32 v7, 31, v6
	v_lshlrev_b64 v[6:7], 10, v[6:7]
	v_lshl_add_u64 v[92:93], v[90:91], 0, v[6:7]
	v_sub_u32_e64 v6, v1, 9 clamp
	v_or_b32_e32 v6, v6, v18
	v_ashrrev_i32_e32 v7, 31, v6
	v_lshlrev_b64 v[6:7], 10, v[6:7]
	v_lshl_add_u64 v[94:95], v[90:91], 0, v[6:7]
	v_sub_u32_e64 v6, v1, 8 clamp
	v_or_b32_e32 v6, v6, v18
	v_ashrrev_i32_e32 v7, 31, v6
	v_sub_u32_e64 v2, v1, 14 clamp
	v_lshlrev_b64 v[6:7], 10, v[6:7]
	v_or_b32_e32 v2, v2, v18
	v_sub_u32_e64 v4, v1, 13 clamp
	v_lshl_add_u64 v[96:97], v[90:91], 0, v[6:7]
	v_sub_u32_e64 v6, v1, 7 clamp
	v_ashrrev_i32_e32 v3, 31, v2
	v_or_b32_e32 v4, v4, v18
	v_or_b32_e32 v6, v6, v18
	v_lshlrev_b64 v[2:3], 10, v[2:3]
	v_ashrrev_i32_e32 v5, 31, v4
	v_ashrrev_i32_e32 v7, 31, v6
	v_lshl_add_u64 v[2:3], v[90:91], 0, v[2:3]
	v_lshlrev_b64 v[4:5], 10, v[4:5]
	v_lshlrev_b64 v[6:7], 10, v[6:7]
	v_lshl_add_u64 v[4:5], v[90:91], 0, v[4:5]
	v_lshl_add_u64 v[100:101], v[90:91], 0, v[6:7]
	global_load_dword v153, v[2:3], off
	global_load_dword v150, v[4:5], off
	global_load_dword v146, v[8:9], off
	global_load_dword v21, v[12:13], off
	global_load_dword v17, v[92:93], off
	global_load_dword v14, v[94:95], off
	global_load_dword v10, v[96:97], off
	global_load_dword v7, v[100:101], off
	v_sub_u32_e64 v2, v1, 6 clamp
	v_or_b32_e32 v2, v2, v18
	v_ashrrev_i32_e32 v3, 31, v2
	v_lshlrev_b64 v[2:3], 10, v[2:3]
	v_lshl_add_u64 v[4:5], v[90:91], 0, v[2:3]
	v_sub_u32_e64 v2, v1, 5 clamp
	v_or_b32_e32 v2, v2, v18
	v_ashrrev_i32_e32 v3, 31, v2
	v_lshlrev_b64 v[2:3], 10, v[2:3]
	v_lshl_add_u64 v[92:93], v[90:91], 0, v[2:3]
	v_sub_u32_e64 v2, v1, 4 clamp
	v_or_b32_e32 v2, v2, v18
	v_ashrrev_i32_e32 v3, 31, v2
	v_lshlrev_b64 v[2:3], 10, v[2:3]
	v_lshl_add_u64 v[94:95], v[90:91], 0, v[2:3]
	v_sub_u32_e64 v2, v1, 3 clamp
	v_or_b32_e32 v2, v2, v18
	v_ashrrev_i32_e32 v3, 31, v2
	v_lshlrev_b64 v[2:3], 10, v[2:3]
	v_lshl_add_u64 v[96:97], v[90:91], 0, v[2:3]
	v_sub_u32_e64 v2, v1, 2 clamp
	v_or_b32_e32 v2, v2, v18
	v_ashrrev_i32_e32 v3, 31, v2
	v_lshlrev_b64 v[2:3], 10, v[2:3]
	v_sub_u32_e64 v1, v1, 1 clamp
	v_lshl_add_u64 v[100:101], v[90:91], 0, v[2:3]
	v_or_b32_e32 v2, v1, v18
	v_ashrrev_i32_e32 v3, 31, v2
	v_lshlrev_b64 v[2:3], 10, v[2:3]
	v_ashrrev_i32_e32 v1, 31, v0
	v_lshl_add_u64 v[102:103], v[90:91], 0, v[2:3]
	v_lshlrev_b64 v[2:3], 10, v[0:1]
	v_lshl_add_u64 v[104:105], v[90:91], 0, v[2:3]
	v_or_b32_e32 v2, 1, v0
	v_ashrrev_i32_e32 v3, 31, v2
	v_lshlrev_b64 v[2:3], 10, v[2:3]
	v_lshl_add_u64 v[106:107], v[90:91], 0, v[2:3]
	global_load_dword v145, v[4:5], off
	global_load_dword v20, v[92:93], off
	global_load_dword v18, v[94:95], off
	global_load_dword v16, v[96:97], off
	global_load_dword v12, v[100:101], off
	global_load_dword v8, v[102:103], off
	global_load_dword v3, v[104:105], off
	global_load_dword v2, v[106:107], off
	v_or_b32_e32 v4, 2, v0
	v_ashrrev_i32_e32 v5, 31, v4
	v_lshlrev_b64 v[4:5], 10, v[4:5]
	v_lshl_add_u64 v[92:93], v[90:91], 0, v[4:5]
	v_or_b32_e32 v4, 3, v0
	v_ashrrev_i32_e32 v5, 31, v4
	v_lshlrev_b64 v[4:5], 10, v[4:5]
	v_lshl_add_u64 v[94:95], v[90:91], 0, v[4:5]
	v_or_b32_e32 v4, 4, v0
	v_ashrrev_i32_e32 v5, 31, v4
	v_lshlrev_b64 v[4:5], 10, v[4:5]
	v_lshl_add_u64 v[96:97], v[90:91], 0, v[4:5]
	v_or_b32_e32 v4, 5, v0
	v_ashrrev_i32_e32 v5, 31, v4
	v_lshlrev_b64 v[4:5], 10, v[4:5]
	v_lshl_add_u64 v[100:101], v[90:91], 0, v[4:5]
	v_or_b32_e32 v4, 6, v0
	v_or_b32_e32 v0, 7, v0
	v_ashrrev_i32_e32 v5, 31, v4
	v_ashrrev_i32_e32 v1, 31, v0
	v_lshlrev_b64 v[4:5], 10, v[4:5]
; #define CONV_LOAD(dst, it_) do { const int t0_ = (it_) * 16 + th * 8, tb_ = t0_ & (SEQ - 1); \
;         _Pragma("unroll") for (int r = 0; r < 38; ++r) { const int pos = tb_ - 30 + r; dst[r] = *(const unsigned*)(VC + (size_t)(t0_ - tb_ + (pos < 0 ? 0 : pos)) * CONVC + 2 * cp); } } while (0)
; __device__ __forceinline__ void conv_phase(LAS unsigned char* lds, const bf16_t* VC, const float* cw, const float* cb, const float* lng, const float* lnb, bf16_t* CAT, int tid, int lane, int wave) {
;     ...
;     for (int it = blockIdx.x; it < T / 16; it += gridDim.x) {
;         const int t0 = it * 16 + th * 8, tb = t0 & (SEQ - 1);
;         f32x2v av[8];
; #pragma unroll
;         for (int t = 0; t < 8; ++t) av[t] = bias;
;         unsigned vv[38];
; #pragma unroll
;         for (int r = 0; r < 38; ++r) vv[r] = vn[r];
;         if (it + (int)gridDim.x < T / 16) CONV_LOAD(vn, it + (int)gridDim.x);
; #pragma unroll
;         for (int r = 0; r < 38; ++r) {
;             const unsigned v = (tb - 30 + r >= 0) ? vv[r] : 0u;
;             const f32x2v vf = {bf_lo(v), bf_hi(v)};
; #pragma unroll
;             for (int t = 0; t < 8; ++t) { const int k = r - t; if (k >= 0 && k < TAPS) av[t] = __builtin_elementwise_fma(wk[k], vf, av[t]); }
	v_lshlrev_b64 v[0:1], 10, v[0:1]
	v_lshl_add_u64 v[102:103], v[90:91], 0, v[4:5]
	v_lshl_add_u64 v[0:1], v[90:91], 0, v[0:1]
	global_load_dword v13, v[92:93], off
	global_load_dword v11, v[94:95], off
	global_load_dword v9, v[96:97], off
	global_load_dword v6, v[100:101], off
	global_load_dword v5, v[102:103], off
	global_load_dword v4, v[0:1], off
	v_mbcnt_lo_u32_b32 v0, -1, 0
	v_mbcnt_hi_u32_b32 v103, -1, v0
	v_and_b32_e32 v0, 64, v103
	v_add_u32_e32 v104, 64, v0
	v_lshlrev_b32_e32 v0, 4, v196
	v_mov_b32_e32 v1, v25
	v_lshl_add_u64 v[96:97], s[42:43], 0, v[0:1]
	v_xor_b32_e32 v1, 1, v103
	v_cmp_lt_i32_e32 vcc, v1, v104
	v_add_u32_e32 v105, 0, v24
	v_lshlrev_b32_e32 v24, 5, v196
	v_cndmask_b32_e32 v1, v103, v1, vcc
	v_lshl_add_u64 v[92:93], s[14:15], 0, v[24:25]
	v_lshl_add_u64 v[94:95], s[16:17], 0, v[24:25]
	v_lshlrev_b32_e32 v25, 2, v1
	v_xor_b32_e32 v1, 2, v103
	v_cmp_lt_i32_e32 vcc, v1, v104
	v_lshlrev_b32_e32 v0, 14, v99
	s_lshl_b32 s15, s22, 4
	v_cndmask_b32_e32 v1, v103, v1, vcc
	v_lshlrev_b32_e32 v99, 2, v1
	v_xor_b32_e32 v1, 4, v103
	v_cmp_lt_i32_e32 vcc, v1, v104
	s_add_i32 s5, s0, 0
	s_lshl_b32 s14, s1, 1
	v_cndmask_b32_e32 v1, v103, v1, vcc
	v_lshlrev_b32_e32 v100, 2, v1
	v_xor_b32_e32 v1, 8, v103
	v_cmp_lt_i32_e32 vcc, v1, v104
	v_add_u32_e32 v105, v105, v0
	s_mov_b32 s4, 0x3b000000
	v_cndmask_b32_e32 v1, v103, v1, vcc
	v_lshlrev_b32_e32 v101, 2, v1
	v_xor_b32_e32 v1, 16, v103
	v_cmp_lt_i32_e32 vcc, v1, v104
	s_mov_b32 s16, 0xf800000
	v_mov_b32_e32 v106, 0x260
	v_cndmask_b32_e32 v1, v103, v1, vcc
	v_lshlrev_b32_e32 v102, 2, v1
	v_xor_b32_e32 v1, 32, v103
	v_cmp_lt_i32_e32 vcc, v1, v104
	v_add_u32_e32 v104, s15, v98
	s_mov_b32 s17, s2
	v_cndmask_b32_e32 v1, v103, v1, vcc
	v_lshlrev_b32_e32 v103, 2, v1
	s_waitcnt vmcnt(0)
	v_mov_b32_e32 v107, v159
	v_mov_b32_e32 v108, v158
	v_mov_b32_e32 v109, v156
	v_mov_b32_e32 v110, v155
	v_mov_b32_e32 v111, v152
	v_mov_b32_e32 v112, v149
	v_mov_b32_e32 v113, v147
	v_mov_b32_e32 v114, v23
	v_mov_b32_e32 v115, v160
	v_mov_b32_e32 v116, v157
	v_mov_b32_e32 v117, v154
	v_mov_b32_e32 v118, v151
	v_mov_b32_e32 v119, v148
	v_mov_b32_e32 v120, v22
	v_mov_b32_e32 v121, v19
	v_mov_b32_e32 v122, v15
	v_mov_b32_e32 v123, v153
	v_mov_b32_e32 v124, v150
	v_mov_b32_e32 v125, v146
	v_mov_b32_e32 v126, v21
	v_mov_b32_e32 v127, v17
	v_mov_b32_e32 v128, v14
	v_mov_b32_e32 v129, v10
	v_mov_b32_e32 v130, v7
	v_mov_b32_e32 v131, v145
	v_mov_b32_e32 v132, v20
	v_mov_b32_e32 v133, v18
	v_mov_b32_e32 v134, v16
	v_mov_b32_e32 v135, v12
	v_mov_b32_e32 v136, v8
	v_mov_b32_e32 v137, v3
	v_mov_b32_e32 v138, v2
	v_mov_b32_e32 v139, v13
	v_mov_b32_e32 v140, v11
	v_mov_b32_e32 v141, v9
	v_mov_b32_e32 v142, v6
	v_mov_b32_e32 v143, v5
	v_mov_b32_e32 v144, v4
	v_readlane_b32 s54, v249, 8
	v_readlane_b32 s55, v249, 9
	v_readlane_b32 s56, v249, 10
	v_readlane_b32 s57, v249, 11
	v_readlane_b32 s58, v249, 12
	v_readlane_b32 s59, v249, 13
	v_readlane_b32 s60, v249, 14
	v_readlane_b32 s61, v249, 15
	v_readlane_b32 s62, v249, 16
	v_readlane_b32 s63, v249, 17
	s_branch .LBB0_483
.LBB0_482:
	s_bfe_u32 s98, s3, 0x30004
	s_lshl_b32 s98, s98, 12
	s_lshr_b32 s99, s3, 7
	s_lshl_b32 s99, s99, 4
	s_or_b32 s98, s98, s99
	v_add_u32_e32 v0, s98, v98
	v_and_b32_e32 v174, 0x7f8, v0
	v_cmp_lt_u32_e32 vcc, 29, v174
	s_add_i32 s12, s14, s98
	s_ashr_i32 s13, s12, 31
	v_cndmask_b32_e32 v1, 0, v159, vcc
	v_cmp_lt_u32_e32 vcc, 28, v174
	v_lshlrev_b32_e32 v0, 16, v1
	v_and_b32_e32 v1, 0xffff0000, v1
	v_cndmask_b32_e32 v159, 0, v158, vcc
	v_cmp_lt_u32_e32 vcc, 27, v174
	v_pk_fma_f32 v[0:1], v[84:85], v[0:1], v[88:89]
	v_lshlrev_b32_e32 v158, 16, v159
	v_and_b32_e32 v159, 0xffff0000, v159
	v_cndmask_b32_e32 v156, 0, v156, vcc
	v_cmp_lt_u32_e32 vcc, 26, v174
	v_pk_fma_f32 v[0:1], v[86:87], v[158:159], v[0:1]
	v_pk_fma_f32 v[158:159], v[84:85], v[158:159], v[88:89]
	v_lshlrev_b32_e32 v162, 16, v156
	v_and_b32_e32 v163, 0xffff0000, v156
	v_cndmask_b32_e32 v155, 0, v155, vcc
	v_cmp_lt_u32_e32 vcc, 25, v174
	v_pk_fma_f32 v[0:1], v[26:27], v[162:163], v[0:1]
	v_pk_fma_f32 v[158:159], v[86:87], v[162:163], v[158:159]
	v_pk_fma_f32 v[162:163], v[84:85], v[162:163], v[88:89]
	v_lshlrev_b32_e32 v164, 16, v155
	v_and_b32_e32 v165, 0xffff0000, v155
	v_cndmask_b32_e32 v152, 0, v152, vcc
	v_cmp_lt_u32_e32 vcc, 24, v174
	v_pk_fma_f32 v[0:1], v[28:29], v[164:165], v[0:1]
	v_pk_fma_f32 v[158:159], v[26:27], v[164:165], v[158:159]
	v_pk_fma_f32 v[162:163], v[86:87], v[164:165], v[162:163]
	v_pk_fma_f32 v[164:165], v[84:85], v[164:165], v[88:89]
	v_lshlrev_b32_e32 v166, 16, v152
	v_and_b32_e32 v167, 0xffff0000, v152
	v_cndmask_b32_e32 v149, 0, v149, vcc
	v_cmp_lt_u32_e32 vcc, 23, v174
	v_pk_fma_f32 v[0:1], v[30:31], v[166:167], v[0:1]
	v_pk_fma_f32 v[158:159], v[28:29], v[166:167], v[158:159]
	v_pk_fma_f32 v[162:163], v[26:27], v[166:167], v[162:163]
	v_pk_fma_f32 v[164:165], v[86:87], v[166:167], v[164:165]
	v_pk_fma_f32 v[166:167], v[84:85], v[166:167], v[88:89]
	v_lshlrev_b32_e32 v168, 16, v149
	v_and_b32_e32 v169, 0xffff0000, v149
	v_cndmask_b32_e32 v147, 0, v147, vcc
	v_cmp_lt_u32_e32 vcc, 22, v174
	v_pk_fma_f32 v[0:1], v[32:33], v[168:169], v[0:1]
	v_pk_fma_f32 v[158:159], v[30:31], v[168:169], v[158:159]
	v_pk_fma_f32 v[162:163], v[28:29], v[168:169], v[162:163]
	v_pk_fma_f32 v[164:165], v[26:27], v[168:169], v[164:165]
	v_pk_fma_f32 v[166:167], v[86:87], v[168:169], v[166:167]
	v_pk_fma_f32 v[168:169], v[84:85], v[168:169], v[88:89]
	v_lshlrev_b32_e32 v170, 16, v147
	v_and_b32_e32 v171, 0xffff0000, v147
	v_cndmask_b32_e32 v23, 0, v23, vcc
	v_cmp_lt_u32_e32 vcc, 21, v174
	v_pk_fma_f32 v[0:1], v[34:35], v[170:171], v[0:1]
	v_pk_fma_f32 v[158:159], v[32:33], v[170:171], v[158:159]
; __device__ __forceinline__ void conv_phase(LAS unsigned char* lds, const bf16_t* VC, const float* cw, const float* cb, const float* lng, const float* lnb, bf16_t* CAT, int tid, int lane, int wave) {
;     ...
;         for (int r = 0; r < 38; ++r) {
;             const unsigned v = (tb - 30 + r >= 0) ? vv[r] : 0u;
;             const f32x2v vf = {bf_lo(v), bf_hi(v)};
; #pragma unroll
;             for (int t = 0; t < 8; ++t) { const int k = r - t; if (k >= 0 && k < TAPS) av[t] = __builtin_elementwise_fma(wk[k], vf, av[t]); }
	v_pk_fma_f32 v[162:163], v[30:31], v[170:171], v[162:163]
	v_pk_fma_f32 v[164:165], v[28:29], v[170:171], v[164:165]
	v_pk_fma_f32 v[166:167], v[26:27], v[170:171], v[166:167]
	v_pk_fma_f32 v[168:169], v[86:87], v[170:171], v[168:169]
	v_pk_fma_f32 v[170:171], v[84:85], v[170:171], v[88:89]
	v_lshlrev_b32_e32 v172, 16, v23
	v_and_b32_e32 v173, 0xffff0000, v23
	v_cndmask_b32_e32 v23, 0, v160, vcc
	v_cmp_lt_u32_e32 vcc, 20, v174
	v_pk_fma_f32 v[0:1], v[36:37], v[172:173], v[0:1]
	v_pk_fma_f32 v[158:159], v[34:35], v[172:173], v[158:159]
	v_pk_fma_f32 v[162:163], v[32:33], v[172:173], v[162:163]
	v_pk_fma_f32 v[164:165], v[30:31], v[172:173], v[164:165]
	v_pk_fma_f32 v[166:167], v[28:29], v[172:173], v[166:167]
	v_pk_fma_f32 v[168:169], v[26:27], v[172:173], v[168:169]
	v_pk_fma_f32 v[170:171], v[86:87], v[172:173], v[170:171]
	v_pk_fma_f32 v[172:173], v[84:85], v[172:173], v[88:89]
	v_lshlrev_b32_e32 v160, 16, v23
	v_and_b32_e32 v161, 0xffff0000, v23
	v_cndmask_b32_e32 v23, 0, v157, vcc
	v_cmp_lt_u32_e32 vcc, 19, v174
	v_pk_fma_f32 v[0:1], v[38:39], v[160:161], v[0:1]
	v_pk_fma_f32 v[158:159], v[36:37], v[160:161], v[158:159]
	v_pk_fma_f32 v[162:163], v[34:35], v[160:161], v[162:163]
	v_pk_fma_f32 v[164:165], v[32:33], v[160:161], v[164:165]
	v_pk_fma_f32 v[166:167], v[30:31], v[160:161], v[166:167]
	v_pk_fma_f32 v[168:169], v[28:29], v[160:161], v[168:169]
	v_pk_fma_f32 v[170:171], v[26:27], v[160:161], v[170:171]
	v_pk_fma_f32 v[160:161], v[86:87], v[160:161], v[172:173]
	v_lshlrev_b32_e32 v156, 16, v23
	v_and_b32_e32 v157, 0xffff0000, v23
	v_cndmask_b32_e32 v23, 0, v154, vcc
	v_cmp_lt_u32_e32 vcc, 18, v174
	v_pk_fma_f32 v[0:1], v[40:41], v[156:157], v[0:1]
	v_pk_fma_f32 v[158:159], v[38:39], v[156:157], v[158:159]
	v_pk_fma_f32 v[162:163], v[36:37], v[156:157], v[162:163]
	v_pk_fma_f32 v[164:165], v[34:35], v[156:157], v[164:165]
	v_pk_fma_f32 v[166:167], v[32:33], v[156:157], v[166:167]
	v_pk_fma_f32 v[168:169], v[30:31], v[156:157], v[168:169]
	v_pk_fma_f32 v[170:171], v[28:29], v[156:157], v[170:171]
	v_pk_fma_f32 v[156:157], v[26:27], v[156:157], v[160:161]
	v_lshlrev_b32_e32 v154, 16, v23
	v_and_b32_e32 v155, 0xffff0000, v23
	v_cndmask_b32_e32 v23, 0, v151, vcc
	v_cmp_lt_u32_e32 vcc, 17, v174
	v_pk_fma_f32 v[0:1], v[42:43], v[154:155], v[0:1]
	v_pk_fma_f32 v[158:159], v[40:41], v[154:155], v[158:159]
	v_pk_fma_f32 v[160:161], v[38:39], v[154:155], v[162:163]
	v_pk_fma_f32 v[162:163], v[36:37], v[154:155], v[164:165]
	v_pk_fma_f32 v[164:165], v[34:35], v[154:155], v[166:167]
	v_pk_fma_f32 v[166:167], v[32:33], v[154:155], v[168:169]
	v_pk_fma_f32 v[168:169], v[30:31], v[154:155], v[170:171]
	v_pk_fma_f32 v[154:155], v[28:29], v[154:155], v[156:157]
	v_lshlrev_b32_e32 v156, 16, v23
	v_and_b32_e32 v157, 0xffff0000, v23
	v_cndmask_b32_e32 v23, 0, v148, vcc
	v_cmp_lt_u32_e32 vcc, 16, v174
	v_pk_fma_f32 v[0:1], v[44:45], v[156:157], v[0:1]
	v_pk_fma_f32 v[158:159], v[42:43], v[156:157], v[158:159]
	v_pk_fma_f32 v[160:161], v[40:41], v[156:157], v[160:161]
	v_pk_fma_f32 v[162:163], v[38:39], v[156:157], v[162:163]
	v_pk_fma_f32 v[164:165], v[36:37], v[156:157], v[164:165]
	v_pk_fma_f32 v[166:167], v[34:35], v[156:157], v[166:167]
	v_pk_fma_f32 v[168:169], v[32:33], v[156:157], v[168:169]
	v_pk_fma_f32 v[154:155], v[30:31], v[156:157], v[154:155]
	v_lshlrev_b32_e32 v148, 16, v23
	v_and_b32_e32 v149, 0xffff0000, v23
	v_cndmask_b32_e32 v23, 0, v22, vcc
	v_cmp_lt_u32_e32 vcc, 15, v174
	v_pk_fma_f32 v[0:1], v[46:47], v[148:149], v[0:1]
	v_pk_fma_f32 v[156:157], v[44:45], v[148:149], v[158:159]
	v_pk_fma_f32 v[158:159], v[42:43], v[148:149], v[160:161]
	v_pk_fma_f32 v[160:161], v[40:41], v[148:149], v[162:163]
	v_pk_fma_f32 v[162:163], v[38:39], v[148:149], v[164:165]
	v_pk_fma_f32 v[164:165], v[36:37], v[148:149], v[166:167]
	v_pk_fma_f32 v[166:167], v[34:35], v[148:149], v[168:169]
	v_pk_fma_f32 v[148:149], v[32:33], v[148:149], v[154:155]
	v_lshlrev_b32_e32 v22, 16, v23
	v_and_b32_e32 v23, 0xffff0000, v23
	v_cndmask_b32_e32 v19, 0, v19, vcc
	v_cmp_lt_u32_e32 vcc, 14, v174
	v_pk_fma_f32 v[0:1], v[48:49], v[22:23], v[0:1]
	v_pk_fma_f32 v[154:155], v[46:47], v[22:23], v[156:157]
	v_pk_fma_f32 v[156:157], v[44:45], v[22:23], v[158:159]
	v_pk_fma_f32 v[158:159], v[42:43], v[22:23], v[160:161]
	v_pk_fma_f32 v[160:161], v[40:41], v[22:23], v[162:163]
	v_pk_fma_f32 v[162:163], v[38:39], v[22:23], v[164:165]
	v_pk_fma_f32 v[164:165], v[36:37], v[22:23], v[166:167]
	v_pk_fma_f32 v[22:23], v[34:35], v[22:23], v[148:149]
	v_lshlrev_b32_e32 v148, 16, v19
	v_and_b32_e32 v149, 0xffff0000, v19
	v_cndmask_b32_e32 v15, 0, v15, vcc
	v_cmp_lt_u32_e32 vcc, 13, v174
	v_pk_fma_f32 v[0:1], v[50:51], v[148:149], v[0:1]
	v_pk_fma_f32 v[154:155], v[48:49], v[148:149], v[154:155]
	v_pk_fma_f32 v[156:157], v[46:47], v[148:149], v[156:157]
	v_pk_fma_f32 v[158:159], v[44:45], v[148:149], v[158:159]
	v_pk_fma_f32 v[160:161], v[42:43], v[148:149], v[160:161]
	v_pk_fma_f32 v[162:163], v[40:41], v[148:149], v[162:163]
	v_pk_fma_f32 v[164:165], v[38:39], v[148:149], v[164:165]
	v_pk_fma_f32 v[22:23], v[36:37], v[148:149], v[22:23]
	v_lshlrev_b32_e32 v148, 16, v15
	v_and_b32_e32 v149, 0xffff0000, v15
	v_cndmask_b32_e32 v15, 0, v153, vcc
	v_cmp_lt_u32_e32 vcc, 12, v174
	v_pk_fma_f32 v[0:1], v[52:53], v[148:149], v[0:1]
	v_pk_fma_f32 v[154:155], v[50:51], v[148:149], v[154:155]
	v_pk_fma_f32 v[156:157], v[48:49], v[148:149], v[156:157]
	v_pk_fma_f32 v[158:159], v[46:47], v[148:149], v[158:159]
	v_pk_fma_f32 v[160:161], v[44:45], v[148:149], v[160:161]
	v_pk_fma_f32 v[162:163], v[42:43], v[148:149], v[162:163]
	v_pk_fma_f32 v[164:165], v[40:41], v[148:149], v[164:165]
; __device__ __forceinline__ void conv_phase(LAS unsigned char* lds, const bf16_t* VC, const float* cw, const float* cb, const float* lng, const float* lnb, bf16_t* CAT, int tid, int lane, int wave) {
;     ...
;         for (int r = 0; r < 38; ++r) {
;             const unsigned v = (tb - 30 + r >= 0) ? vv[r] : 0u;
;             const f32x2v vf = {bf_lo(v), bf_hi(v)};
; #pragma unroll
;             for (int t = 0; t < 8; ++t) { const int k = r - t; if (k >= 0 && k < TAPS) av[t] = __builtin_elementwise_fma(wk[k], vf, av[t]); }
	v_pk_fma_f32 v[22:23], v[38:39], v[148:149], v[22:23]
	v_lshlrev_b32_e32 v148, 16, v15
	v_and_b32_e32 v149, 0xffff0000, v15
	v_cndmask_b32_e32 v15, 0, v150, vcc
	v_cmp_lt_u32_e32 vcc, 11, v174
	v_pk_fma_f32 v[0:1], v[54:55], v[148:149], v[0:1]
	v_pk_fma_f32 v[152:153], v[52:53], v[148:149], v[154:155]
	v_pk_fma_f32 v[154:155], v[50:51], v[148:149], v[156:157]
	v_pk_fma_f32 v[156:157], v[48:49], v[148:149], v[158:159]
	v_pk_fma_f32 v[158:159], v[46:47], v[148:149], v[160:161]
	v_pk_fma_f32 v[160:161], v[44:45], v[148:149], v[162:163]
	v_pk_fma_f32 v[162:163], v[42:43], v[148:149], v[164:165]
	v_pk_fma_f32 v[22:23], v[40:41], v[148:149], v[22:23]
	v_lshlrev_b32_e32 v148, 16, v15
	v_and_b32_e32 v149, 0xffff0000, v15
	v_cndmask_b32_e32 v15, 0, v146, vcc
	v_cmp_lt_u32_e32 vcc, 10, v174
	v_pk_fma_f32 v[0:1], v[56:57], v[148:149], v[0:1]
	v_pk_fma_f32 v[150:151], v[54:55], v[148:149], v[152:153]
	v_pk_fma_f32 v[152:153], v[52:53], v[148:149], v[154:155]
	v_pk_fma_f32 v[154:155], v[50:51], v[148:149], v[156:157]
	v_pk_fma_f32 v[156:157], v[48:49], v[148:149], v[158:159]
	v_pk_fma_f32 v[158:159], v[46:47], v[148:149], v[160:161]
	v_pk_fma_f32 v[160:161], v[44:45], v[148:149], v[162:163]
	v_pk_fma_f32 v[22:23], v[42:43], v[148:149], v[22:23]
	v_lshlrev_b32_e32 v146, 16, v15
	v_and_b32_e32 v147, 0xffff0000, v15
	v_cndmask_b32_e32 v15, 0, v21, vcc
	v_cmp_lt_u32_e32 vcc, 9, v174
	v_pk_fma_f32 v[0:1], v[58:59], v[146:147], v[0:1]
	v_pk_fma_f32 v[148:149], v[56:57], v[146:147], v[150:151]
	v_pk_fma_f32 v[150:151], v[54:55], v[146:147], v[152:153]
	v_pk_fma_f32 v[152:153], v[52:53], v[146:147], v[154:155]
	v_pk_fma_f32 v[154:155], v[50:51], v[146:147], v[156:157]
	v_pk_fma_f32 v[156:157], v[48:49], v[146:147], v[158:159]
	v_pk_fma_f32 v[158:159], v[46:47], v[146:147], v[160:161]
	v_pk_fma_f32 v[22:23], v[44:45], v[146:147], v[22:23]
	v_lshlrev_b32_e32 v146, 16, v15
	v_and_b32_e32 v147, 0xffff0000, v15
	v_cndmask_b32_e32 v15, 0, v17, vcc
	v_cmp_lt_u32_e32 vcc, 8, v174
	v_pk_fma_f32 v[0:1], v[60:61], v[146:147], v[0:1]
	v_pk_fma_f32 v[148:149], v[58:59], v[146:147], v[148:149]
	v_pk_fma_f32 v[150:151], v[56:57], v[146:147], v[150:151]
	v_pk_fma_f32 v[152:153], v[54:55], v[146:147], v[152:153]
	v_pk_fma_f32 v[154:155], v[52:53], v[146:147], v[154:155]
	v_pk_fma_f32 v[156:157], v[50:51], v[146:147], v[156:157]
	v_pk_fma_f32 v[158:159], v[48:49], v[146:147], v[158:159]
	v_pk_fma_f32 v[22:23], v[46:47], v[146:147], v[22:23]
	v_lshlrev_b32_e32 v146, 16, v15
	v_and_b32_e32 v147, 0xffff0000, v15
	v_cndmask_b32_e32 v15, 0, v14, vcc
	v_cmp_eq_u32_e32 vcc, 0, v174
	v_pk_fma_f32 v[0:1], v[62:63], v[146:147], v[0:1]
	v_pk_fma_f32 v[148:149], v[60:61], v[146:147], v[148:149]
	v_pk_fma_f32 v[150:151], v[58:59], v[146:147], v[150:151]
	v_pk_fma_f32 v[152:153], v[56:57], v[146:147], v[152:153]
	v_pk_fma_f32 v[154:155], v[54:55], v[146:147], v[154:155]
	v_pk_fma_f32 v[156:157], v[52:53], v[146:147], v[156:157]
	v_pk_fma_f32 v[158:159], v[50:51], v[146:147], v[158:159]
	v_pk_fma_f32 v[22:23], v[48:49], v[146:147], v[22:23]
	v_lshlrev_b32_e32 v14, 16, v15
	v_and_b32_e32 v15, 0xffff0000, v15
	v_cndmask_b32_e64 v10, v10, 0, vcc
	v_pk_fma_f32 v[0:1], v[64:65], v[14:15], v[0:1]
	v_pk_fma_f32 v[146:147], v[62:63], v[14:15], v[148:149]
	v_pk_fma_f32 v[148:149], v[60:61], v[14:15], v[150:151]
	v_pk_fma_f32 v[150:151], v[58:59], v[14:15], v[152:153]
	v_pk_fma_f32 v[152:153], v[56:57], v[14:15], v[154:155]
	v_pk_fma_f32 v[154:155], v[54:55], v[14:15], v[156:157]
	v_pk_fma_f32 v[156:157], v[52:53], v[14:15], v[158:159]
	v_pk_fma_f32 v[14:15], v[50:51], v[14:15], v[22:23]
	v_lshlrev_b32_e32 v22, 16, v10
	v_and_b32_e32 v23, 0xffff0000, v10
	v_cndmask_b32_e64 v7, v7, 0, vcc
	v_pk_fma_f32 v[0:1], v[66:67], v[22:23], v[0:1]
	v_pk_fma_f32 v[146:147], v[64:65], v[22:23], v[146:147]
	v_pk_fma_f32 v[148:149], v[62:63], v[22:23], v[148:149]
	v_pk_fma_f32 v[150:151], v[60:61], v[22:23], v[150:151]
	v_pk_fma_f32 v[152:153], v[58:59], v[22:23], v[152:153]
	v_pk_fma_f32 v[154:155], v[56:57], v[22:23], v[154:155]
	v_pk_fma_f32 v[156:157], v[54:55], v[22:23], v[156:157]
	v_pk_fma_f32 v[14:15], v[52:53], v[22:23], v[14:15]
	v_lshlrev_b32_e32 v22, 16, v7
	v_and_b32_e32 v23, 0xffff0000, v7
	v_cndmask_b32_e64 v7, v145, 0, vcc
	v_pk_fma_f32 v[0:1], v[68:69], v[22:23], v[0:1]
	v_pk_fma_f32 v[146:147], v[66:67], v[22:23], v[146:147]
	v_pk_fma_f32 v[148:149], v[64:65], v[22:23], v[148:149]
	v_pk_fma_f32 v[150:151], v[62:63], v[22:23], v[150:151]
	v_pk_fma_f32 v[152:153], v[60:61], v[22:23], v[152:153]
	v_pk_fma_f32 v[154:155], v[58:59], v[22:23], v[154:155]
	v_pk_fma_f32 v[156:157], v[56:57], v[22:23], v[156:157]
	v_pk_fma_f32 v[14:15], v[54:55], v[22:23], v[14:15]
	v_lshlrev_b32_e32 v22, 16, v7
	v_and_b32_e32 v23, 0xffff0000, v7
	v_cndmask_b32_e64 v7, v20, 0, vcc
	v_pk_fma_f32 v[0:1], v[70:71], v[22:23], v[0:1]
	v_pk_fma_f32 v[146:147], v[68:69], v[22:23], v[146:147]
	v_pk_fma_f32 v[148:149], v[66:67], v[22:23], v[148:149]
	v_pk_fma_f32 v[150:151], v[64:65], v[22:23], v[150:151]
	v_pk_fma_f32 v[152:153], v[62:63], v[22:23], v[152:153]
	v_pk_fma_f32 v[154:155], v[60:61], v[22:23], v[154:155]
	v_pk_fma_f32 v[156:157], v[58:59], v[22:23], v[156:157]
	v_pk_fma_f32 v[14:15], v[56:57], v[22:23], v[14:15]
	v_lshlrev_b32_e32 v20, 16, v7
	v_and_b32_e32 v21, 0xffff0000, v7
	v_cndmask_b32_e64 v7, v18, 0, vcc
	v_pk_fma_f32 v[0:1], v[72:73], v[20:21], v[0:1]
	v_pk_fma_f32 v[22:23], v[70:71], v[20:21], v[146:147]
	v_pk_fma_f32 v[146:147], v[68:69], v[20:21], v[148:149]
	v_pk_fma_f32 v[148:149], v[66:67], v[20:21], v[150:151]
	v_pk_fma_f32 v[150:151], v[64:65], v[20:21], v[152:153]
	v_pk_fma_f32 v[152:153], v[62:63], v[20:21], v[154:155]
; #define LAS __attribute__((address_space(3)))
; __device__ __forceinline__ void conv_phase(LAS unsigned char* lds, const bf16_t* VC, const float* cw, const float* cb, const float* lng, const float* lnb, bf16_t* CAT, int tid, int lane, int wave) {
;     ...
;         for (int r = 0; r < 38; ++r) {
;             const unsigned v = (tb - 30 + r >= 0) ? vv[r] : 0u;
;             const f32x2v vf = {bf_lo(v), bf_hi(v)};
; #pragma unroll
;             for (int t = 0; t < 8; ++t) { const int k = r - t; if (k >= 0 && k < TAPS) av[t] = __builtin_elementwise_fma(wk[k], vf, av[t]); }
;         }
; #pragma unroll
;         for (int t = 0; t < 8; ++t) *(LAS f32x2v*)(ybuf + (th * 8 + t) * CONVC + 2 * cp) = av[t];
;         __syncthreads();
	v_pk_fma_f32 v[154:155], v[60:61], v[20:21], v[156:157]
	v_pk_fma_f32 v[14:15], v[58:59], v[20:21], v[14:15]
	v_lshlrev_b32_e32 v18, 16, v7
	v_and_b32_e32 v19, 0xffff0000, v7
	v_cndmask_b32_e64 v7, v16, 0, vcc
	v_pk_fma_f32 v[0:1], v[74:75], v[18:19], v[0:1]
	v_pk_fma_f32 v[20:21], v[72:73], v[18:19], v[22:23]
	v_pk_fma_f32 v[22:23], v[70:71], v[18:19], v[146:147]
	v_pk_fma_f32 v[146:147], v[68:69], v[18:19], v[148:149]
	v_pk_fma_f32 v[148:149], v[66:67], v[18:19], v[150:151]
	v_pk_fma_f32 v[150:151], v[64:65], v[18:19], v[152:153]
	v_pk_fma_f32 v[152:153], v[62:63], v[18:19], v[154:155]
	v_pk_fma_f32 v[14:15], v[60:61], v[18:19], v[14:15]
	v_lshlrev_b32_e32 v16, 16, v7
	v_and_b32_e32 v17, 0xffff0000, v7
	v_cndmask_b32_e64 v7, v12, 0, vcc
	v_pk_fma_f32 v[0:1], v[76:77], v[16:17], v[0:1]
	v_pk_fma_f32 v[18:19], v[74:75], v[16:17], v[20:21]
	v_pk_fma_f32 v[20:21], v[72:73], v[16:17], v[22:23]
	v_pk_fma_f32 v[22:23], v[70:71], v[16:17], v[146:147]
	v_pk_fma_f32 v[146:147], v[68:69], v[16:17], v[148:149]
	v_pk_fma_f32 v[148:149], v[66:67], v[16:17], v[150:151]
	v_pk_fma_f32 v[150:151], v[64:65], v[16:17], v[152:153]
	v_pk_fma_f32 v[14:15], v[62:63], v[16:17], v[14:15]
	v_lshlrev_b32_e32 v16, 16, v7
	v_and_b32_e32 v17, 0xffff0000, v7
	v_cndmask_b32_e64 v7, v8, 0, vcc
	v_pk_fma_f32 v[0:1], v[78:79], v[16:17], v[0:1]
	v_pk_fma_f32 v[18:19], v[76:77], v[16:17], v[18:19]
	v_pk_fma_f32 v[20:21], v[74:75], v[16:17], v[20:21]
	v_pk_fma_f32 v[22:23], v[72:73], v[16:17], v[22:23]
	v_pk_fma_f32 v[146:147], v[70:71], v[16:17], v[146:147]
	v_pk_fma_f32 v[148:149], v[68:69], v[16:17], v[148:149]
	v_pk_fma_f32 v[150:151], v[66:67], v[16:17], v[150:151]
	v_pk_fma_f32 v[14:15], v[64:65], v[16:17], v[14:15]
	v_lshlrev_b32_e32 v16, 16, v7
	v_and_b32_e32 v17, 0xffff0000, v7
	v_pk_fma_f32 v[0:1], v[80:81], v[16:17], v[0:1]
	v_pk_fma_f32 v[18:19], v[78:79], v[16:17], v[18:19]
	v_pk_fma_f32 v[20:21], v[76:77], v[16:17], v[20:21]
	v_pk_fma_f32 v[22:23], v[74:75], v[16:17], v[22:23]
	v_pk_fma_f32 v[146:147], v[72:73], v[16:17], v[146:147]
	v_pk_fma_f32 v[148:149], v[70:71], v[16:17], v[148:149]
	v_pk_fma_f32 v[150:151], v[68:69], v[16:17], v[150:151]
	v_pk_fma_f32 v[14:15], v[66:67], v[16:17], v[14:15]
	v_lshlrev_b32_e32 v16, 16, v3
	v_and_b32_e32 v17, 0xffff0000, v3
	v_pk_fma_f32 v[0:1], v[82:83], v[16:17], v[0:1]
	v_pk_fma_f32 v[18:19], v[80:81], v[16:17], v[18:19]
	v_pk_fma_f32 v[20:21], v[78:79], v[16:17], v[20:21]
	v_pk_fma_f32 v[22:23], v[76:77], v[16:17], v[22:23]
	v_pk_fma_f32 v[146:147], v[74:75], v[16:17], v[146:147]
	v_pk_fma_f32 v[148:149], v[72:73], v[16:17], v[148:149]
	v_pk_fma_f32 v[150:151], v[70:71], v[16:17], v[150:151]
	v_pk_fma_f32 v[14:15], v[68:69], v[16:17], v[14:15]
	v_lshlrev_b32_e32 v16, 16, v2
	v_and_b32_e32 v17, 0xffff0000, v2
	v_pk_fma_f32 v[2:3], v[82:83], v[16:17], v[18:19]
	v_pk_fma_f32 v[18:19], v[80:81], v[16:17], v[20:21]
	v_pk_fma_f32 v[20:21], v[78:79], v[16:17], v[22:23]
	v_pk_fma_f32 v[22:23], v[76:77], v[16:17], v[146:147]
	v_pk_fma_f32 v[146:147], v[74:75], v[16:17], v[148:149]
	v_pk_fma_f32 v[148:149], v[72:73], v[16:17], v[150:151]
	v_pk_fma_f32 v[14:15], v[70:71], v[16:17], v[14:15]
	v_lshlrev_b32_e32 v12, 16, v13
	v_and_b32_e32 v13, 0xffff0000, v13
	v_pk_fma_f32 v[16:17], v[82:83], v[12:13], v[18:19]
	v_pk_fma_f32 v[18:19], v[80:81], v[12:13], v[20:21]
	v_pk_fma_f32 v[20:21], v[78:79], v[12:13], v[22:23]
	v_pk_fma_f32 v[22:23], v[76:77], v[12:13], v[146:147]
	v_pk_fma_f32 v[146:147], v[74:75], v[12:13], v[148:149]
	v_pk_fma_f32 v[12:13], v[72:73], v[12:13], v[14:15]
	v_lshlrev_b32_e32 v10, 16, v11
	v_and_b32_e32 v11, 0xffff0000, v11
	v_pk_fma_f32 v[14:15], v[82:83], v[10:11], v[18:19]
	v_pk_fma_f32 v[18:19], v[80:81], v[10:11], v[20:21]
	v_pk_fma_f32 v[20:21], v[78:79], v[10:11], v[22:23]
	v_pk_fma_f32 v[22:23], v[76:77], v[10:11], v[146:147]
	v_pk_fma_f32 v[10:11], v[74:75], v[10:11], v[12:13]
	v_lshlrev_b32_e32 v8, 16, v9
	v_and_b32_e32 v9, 0xffff0000, v9
	v_pk_fma_f32 v[12:13], v[82:83], v[8:9], v[18:19]
	v_pk_fma_f32 v[18:19], v[80:81], v[8:9], v[20:21]
	v_pk_fma_f32 v[20:21], v[78:79], v[8:9], v[22:23]
	v_pk_fma_f32 v[8:9], v[76:77], v[8:9], v[10:11]
	v_lshlrev_b32_e32 v10, 16, v6
	v_and_b32_e32 v11, 0xffff0000, v6
	v_pk_fma_f32 v[6:7], v[82:83], v[10:11], v[18:19]
	v_pk_fma_f32 v[18:19], v[80:81], v[10:11], v[20:21]
	v_pk_fma_f32 v[8:9], v[78:79], v[10:11], v[8:9]
	v_lshlrev_b32_e32 v10, 16, v5
	v_and_b32_e32 v11, 0xffff0000, v5
	v_pk_fma_f32 v[18:19], v[82:83], v[10:11], v[18:19]
	v_pk_fma_f32 v[8:9], v[80:81], v[10:11], v[8:9]
	v_lshlrev_b32_e32 v10, 16, v4
	v_and_b32_e32 v11, 0xffff0000, v4
	v_add_u32_e32 v145, s5, v24
	v_pk_fma_f32 v[4:5], v[82:83], v[10:11], v[8:9]
	ds_write2st64_b64 v105, v[0:1], v[2:3] offset1:4
	ds_write2st64_b64 v105, v[16:17], v[14:15] offset0:8 offset1:12
	ds_write2st64_b64 v105, v[12:13], v[6:7] offset0:16 offset1:20
	ds_write2st64_b64 v105, v[18:19], v[4:5] offset0:24 offset1:28
	s_waitcnt lgkmcnt(0)
	s_barrier
; __device__ __forceinline__ unsigned cvt_pk_bf16(float lo, float hi) { unsigned r; asm volatile("v_cvt_pk_bf16_f32 %0, %1, %2" : "=v"(r) : "v"(lo), "v"(hi)); return r; }
; #define LAS __attribute__((address_space(3)))
; __device__ __forceinline__ float fast_silu(float x) { return x * fast_sigmoid(x); }
; __device__ __forceinline__ void conv_phase(LAS unsigned char* lds, const bf16_t* VC, const float* cw, const float* cb, const float* lng, const float* lnb, bf16_t* CAT, int tid, int lane, int wave) {
;     ...
;         {   f32x4 y0[2], y1[2]; float sm[2], sq[2];
; #pragma unroll
;             for (int q = 0; q < 2; ++q) { const LAS float* yr = ybuf + (wave * 2 + q) * CONVC + lane * 8; y0[q] = *(const LAS f32x4*)yr; y1[q] = *(const LAS f32x4*)(yr + 4);
;                 sm[q] = (y0[q].x + y0[q].y) + (y0[q].z + y0[q].w) + (y1[q].x + y1[q].y) + (y1[q].z + y1[q].w);
;                 sq[q] = (y0[q].x * y0[q].x + y0[q].y * y0[q].y) + (y0[q].z * y0[q].z + y0[q].w * y0[q].w) + (y1[q].x * y1[q].x + y1[q].y * y1[q].y) + (y1[q].z * y1[q].z + y1[q].w * y1[q].w); }
; #pragma unroll
;             for (int o = 1; o < 64; o <<= 1) { const float a0 = __shfl_xor(sm[0], o), a1 = __shfl_xor(sq[0], o), a2 = __shfl_xor(sm[1], o), a3 = __shfl_xor(sq[1], o); sm[0] += a0; sq[0] += a1; sm[1] += a2; sq[1] += a3; }
;             const f32x4 g0 = *(const f32x4*)(lng + lane * 8), g1 = *(const f32x4*)(lng + lane * 8 + 4), b0 = *(const f32x4*)(lnb + lane * 8), b1 = *(const f32x4*)(lnb + lane * 8 + 4);
; #pragma unroll
;             for (int q = 0; q < 2; ++q) { const float mu = sm[q] * (1.f / CONVC); const float var = fmaxf(sq[q] * (1.f / CONVC) - mu * mu, 0.f);
;                 const float rs = 1.0f / sqrtf(var + 1e-5f);
;                 const f32x4 z0 = (y0[q] - mu) * rs * g0 + b0, z1 = (y1[q] - mu) * rs * g1 + b1;
;                 u32x4 w; w.x = cvt_pk_bf16(fast_silu(z0.x), fast_silu(z0.y)); w.y = cvt_pk_bf16(fast_silu(z0.z), fast_silu(z0.w)); w.z = cvt_pk_bf16(fast_silu(z1.x), fast_silu(z1.y)); w.w = cvt_pk_bf16(fast_silu(z1.z), fast_silu(z1.w));
;                 *(u32x4*)(CAT + (size_t)(it * 16 + wave * 2 + q) * D + lane * 8) = w; } }
	ds_read_b128 v[146:149], v145
	ds_read_b128 v[150:153], v145 offset:16
	s_add_i32 s3, s3, s15
	s_waitcnt lgkmcnt(1)
	v_mul_f32_e32 v0, v146, v146
	v_mul_f32_e32 v2, v147, v147
	v_mul_f32_e32 v4, v148, v148
	v_mul_f32_e32 v6, v149, v149
	v_mov_b32_e32 v1, v146
	v_mov_b32_e32 v3, v147
	v_mov_b32_e32 v7, v148
	v_mov_b32_e32 v5, v149
	s_waitcnt lgkmcnt(0)
	v_mul_f32_e32 v8, v150, v150
	v_mul_f32_e32 v10, v151, v151
	v_pk_add_f32 v[0:1], v[0:1], v[2:3]
	v_pk_add_f32 v[2:3], v[6:7], v[4:5]
	v_mov_b32_e32 v9, v150
	v_mov_b32_e32 v11, v151
	v_mul_f32_e32 v12, v152, v152
	v_mul_f32_e32 v14, v153, v153
	v_pk_add_f32 v[0:1], v[0:1], v[2:3]
	v_pk_add_f32 v[2:3], v[8:9], v[10:11]
	v_mov_b32_e32 v13, v152
	v_mov_b32_e32 v15, v153
	v_pk_add_f32 v[0:1], v[0:1], v[2:3]
	v_pk_add_f32 v[2:3], v[12:13], v[14:15]
	global_load_dwordx4 v[8:11], v[92:93], off
	global_load_dwordx4 v[12:15], v[94:95], off
	v_pk_add_f32 v[0:1], v[2:3], v[0:1]
	ds_bpermute_b32 v3, v25, v1
	ds_bpermute_b32 v2, v25, v0
	s_waitcnt lgkmcnt(0)
	v_pk_add_f32 v[0:1], v[0:1], v[2:3]
	ds_bpermute_b32 v3, v99, v1
	ds_bpermute_b32 v2, v99, v0
	s_waitcnt lgkmcnt(0)
	v_pk_add_f32 v[16:17], v[0:1], v[2:3]
	ds_bpermute_b32 v19, v100, v17
	ds_bpermute_b32 v18, v100, v16
	global_load_dwordx4 v[0:3], v[92:93], off offset:16
	global_load_dwordx4 v[4:7], v[94:95], off offset:16
	ds_read_b128 v[20:23], v145 offset:2048
	s_waitcnt lgkmcnt(1)
	v_pk_add_f32 v[16:17], v[16:17], v[18:19]
	ds_bpermute_b32 v19, v101, v17
	ds_bpermute_b32 v18, v101, v16
	s_waitcnt lgkmcnt(0)
	v_pk_add_f32 v[16:17], v[16:17], v[18:19]
	ds_bpermute_b32 v19, v102, v17
	ds_bpermute_b32 v18, v102, v16
	s_waitcnt lgkmcnt(0)
	v_pk_add_f32 v[154:155], v[16:17], v[18:19]
	ds_bpermute_b32 v157, v103, v155
	ds_bpermute_b32 v156, v103, v154
	ds_read_b128 v[16:19], v145 offset:2064
	v_mul_f32_e32 v158, v20, v20
	v_mul_f32_e32 v160, v21, v21
	v_mul_f32_e32 v162, v22, v22
	s_waitcnt lgkmcnt(1)
	v_pk_add_f32 v[154:155], v[154:155], v[156:157]
	s_waitcnt lgkmcnt(0)
	v_mul_f32_e32 v156, v16, v16
	v_pk_mul_f32 v[154:155], v[154:155], s[4:5] op_sel_hi:[1,0]
	v_mul_f32_e32 v164, v17, v17
	v_fma_f32 v145, -v155, v155, v154
	v_max_f32_e32 v145, 0, v145
	v_add_f32_e32 v145, 0x3727c5ac, v145
	v_mul_f32_e32 v154, 0x4f800000, v145
	v_cmp_gt_f32_e32 vcc, s16, v145
	v_sub_f32_e32 v147, v147, v155
	v_sub_f32_e32 v146, v146, v155
	v_cndmask_b32_e32 v145, v145, v154, vcc
	v_sqrt_f32_e32 v157, v145
	v_sub_f32_e32 v149, v149, v155
	v_sub_f32_e32 v148, v148, v155
	v_sub_f32_e32 v153, v153, v155
	v_add_u32_e32 v159, -1, v157
	v_fma_f32 v161, -v159, v157, v145
	v_cmp_ge_f32_e64 s[0:1], 0, v161
	v_add_u32_e32 v161, 1, v157
	v_sub_f32_e32 v152, v152, v155
	v_cndmask_b32_e64 v159, v157, v159, s[0:1]
	v_fma_f32 v157, -v161, v157, v145
	v_cmp_lt_f32_e64 s[0:1], 0, v157
	v_sub_f32_e32 v151, v151, v155
	v_sub_f32_e32 v150, v150, v155
	v_cndmask_b32_e64 v157, v159, v161, s[0:1]
	v_mul_f32_e32 v159, 0x37800000, v157
	v_cndmask_b32_e32 v157, v157, v159, vcc
	v_cmp_class_f32_e32 vcc, v145, v106
	v_mul_f32_e32 v154, v23, v23
	v_mul_f32_e32 v166, v18, v18
	v_cndmask_b32_e32 v145, v157, v145, vcc
	v_div_scale_f32 v157, s[0:1], v145, v145, 1.0
	v_rcp_f32_e32 v159, v157
	v_mul_f32_e32 v168, v19, v19
	v_mov_b32_e32 v167, v18
	v_mov_b32_e32 v169, v19
	v_fma_f32 v161, -v157, v159, 1.0
	v_fmac_f32_e32 v159, v161, v159
	v_div_scale_f32 v161, vcc, 1.0, v145, 1.0
	v_mul_f32_e32 v163, v161, v159
	v_fma_f32 v165, -v157, v163, v161
	v_fmac_f32_e32 v163, v165, v159
	v_fma_f32 v157, -v157, v163, v161
	v_div_fmas_f32 v157, v157, v159, v163
	v_div_fixup_f32 v170, v157, v145, 1.0
	v_pk_mul_f32 v[146:147], v[146:147], v[170:171] op_sel_hi:[1,0]
	v_pk_mul_f32 v[148:149], v[148:149], v[170:171] op_sel_hi:[1,0]
	s_waitcnt vmcnt(2)
	v_pk_fma_f32 v[146:147], v[8:9], v[146:147], v[12:13]
	v_pk_fma_f32 v[148:149], v[10:11], v[148:149], v[14:15]
	v_mul_f32_e32 v145, 0xbfb8aa3b, v146
	v_exp_f32_e32 v145, v145
	v_mul_f32_e32 v155, 0xbfb8aa3b, v147
	v_exp_f32_e32 v155, v155
	v_mul_f32_e32 v157, 0xbfb8aa3b, v149
	v_add_f32_e32 v145, 1.0, v145
	v_rcp_f32_e32 v145, v145
	v_exp_f32_e32 v157, v157
	v_pk_mul_f32 v[150:151], v[150:151], v[170:171] op_sel_hi:[1,0]
	v_pk_mul_f32 v[152:153], v[152:153], v[170:171] op_sel_hi:[1,0]
	v_mul_f32_e32 v145, v146, v145
	v_add_f32_e32 v146, 1.0, v155
	v_mul_f32_e32 v155, 0xbfb8aa3b, v148
	v_rcp_f32_e32 v146, v146
	v_exp_f32_e32 v155, v155
	v_mov_b32_e32 v159, v20
	v_mov_b32_e32 v161, v21
	v_mul_f32_e32 v170, v147, v146
	v_add_f32_e32 v146, 1.0, v155
	v_rcp_f32_e32 v171, v146
	v_add_f32_e32 v146, 1.0, v157
	v_mov_b32_e32 v155, v22
	v_mov_b32_e32 v163, v23
	v_rcp_f32_e32 v172, v146
	v_pk_add_f32 v[146:147], v[158:159], v[160:161]
	v_pk_add_f32 v[154:155], v[154:155], v[162:163]
	v_mov_b32_e32 v157, v16
	v_mov_b32_e32 v165, v17
	v_pk_add_f32 v[146:147], v[146:147], v[154:155]
	v_pk_add_f32 v[154:155], v[156:157], v[164:165]
	s_waitcnt vmcnt(0)
	v_pk_fma_f32 v[150:151], v[0:1], v[150:151], v[4:5]
	v_pk_add_f32 v[146:147], v[146:147], v[154:155]
	v_pk_add_f32 v[154:155], v[166:167], v[168:169]
	v_pk_fma_f32 v[152:153], v[2:3], v[152:153], v[6:7]
	v_pk_add_f32 v[154:155], v[154:155], v[146:147]
	ds_bpermute_b32 v157, v25, v155
	ds_bpermute_b32 v156, v25, v154
	v_cvt_pk_bf16_f32 v146, v145, v170
	v_mul_f32_e32 v145, v148, v171
	v_mul_f32_e32 v147, v149, v172
	v_cvt_pk_bf16_f32 v147, v145, v147
	s_waitcnt lgkmcnt(0)
	v_pk_add_f32 v[148:149], v[154:155], v[156:157]
	ds_bpermute_b32 v155, v99, v149
	ds_bpermute_b32 v154, v99, v148
	v_mul_f32_e32 v145, 0xbfb8aa3b, v150
	v_exp_f32_e32 v145, v145
	v_mul_f32_e32 v156, 0xbfb8aa3b, v151
	v_exp_f32_e32 v156, v156
	s_waitcnt lgkmcnt(0)
; __device__ __forceinline__ unsigned cvt_pk_bf16(float lo, float hi) { unsigned r; asm volatile("v_cvt_pk_bf16_f32 %0, %1, %2" : "=v"(r) : "v"(lo), "v"(hi)); return r; }
; #define LAS __attribute__((address_space(3)))
; __device__ __forceinline__ float fast_silu(float x) { return x * fast_sigmoid(x); }
; __device__ __forceinline__ void conv_phase(LAS unsigned char* lds, const bf16_t* VC, const float* cw, const float* cb, const float* lng, const float* lnb, bf16_t* CAT, int tid, int lane, int wave) {
;     ...
;         {   f32x4 y0[2], y1[2]; float sm[2], sq[2];
; #pragma unroll
;             for (int q = 0; q < 2; ++q) { const LAS float* yr = ybuf + (wave * 2 + q) * CONVC + lane * 8; y0[q] = *(const LAS f32x4*)yr; y1[q] = *(const LAS f32x4*)(yr + 4);
;                 sm[q] = (y0[q].x + y0[q].y) + (y0[q].z + y0[q].w) + (y1[q].x + y1[q].y) + (y1[q].z + y1[q].w);
;                 sq[q] = (y0[q].x * y0[q].x + y0[q].y * y0[q].y) + (y0[q].z * y0[q].z + y0[q].w * y0[q].w) + (y1[q].x * y1[q].x + y1[q].y * y1[q].y) + (y1[q].z * y1[q].z + y1[q].w * y1[q].w); }
; #pragma unroll
;             for (int o = 1; o < 64; o <<= 1) { const float a0 = __shfl_xor(sm[0], o), a1 = __shfl_xor(sq[0], o), a2 = __shfl_xor(sm[1], o), a3 = __shfl_xor(sq[1], o); sm[0] += a0; sq[0] += a1; sm[1] += a2; sq[1] += a3; }
;             const f32x4 g0 = *(const f32x4*)(lng + lane * 8), g1 = *(const f32x4*)(lng + lane * 8 + 4), b0 = *(const f32x4*)(lnb + lane * 8), b1 = *(const f32x4*)(lnb + lane * 8 + 4);
; #pragma unroll
;             for (int q = 0; q < 2; ++q) { const float mu = sm[q] * (1.f / CONVC); const float var = fmaxf(sq[q] * (1.f / CONVC) - mu * mu, 0.f);
;                 const float rs = 1.0f / sqrtf(var + 1e-5f);
;                 const f32x4 z0 = (y0[q] - mu) * rs * g0 + b0, z1 = (y1[q] - mu) * rs * g1 + b1;
;                 u32x4 w; w.x = cvt_pk_bf16(fast_silu(z0.x), fast_silu(z0.y)); w.y = cvt_pk_bf16(fast_silu(z0.z), fast_silu(z0.w)); w.z = cvt_pk_bf16(fast_silu(z1.x), fast_silu(z1.y)); w.w = cvt_pk_bf16(fast_silu(z1.z), fast_silu(z1.w));
;                 *(u32x4*)(CAT + (size_t)(it * 16 + wave * 2 + q) * D + lane * 8) = w; } }
;         __syncthreads();
	v_pk_add_f32 v[148:149], v[148:149], v[154:155]
	ds_bpermute_b32 v155, v100, v149
	ds_bpermute_b32 v154, v100, v148
	v_add_f32_e32 v145, 1.0, v145
	v_rcp_f32_e32 v145, v145
	v_add_f32_e32 v156, 1.0, v156
	v_rcp_f32_e32 v156, v156
	s_waitcnt lgkmcnt(0)
	v_pk_add_f32 v[148:149], v[148:149], v[154:155]
	ds_bpermute_b32 v155, v101, v149
	ds_bpermute_b32 v154, v101, v148
	v_mul_f32_e32 v145, v150, v145
	v_mul_f32_e32 v150, 0xbfb8aa3b, v152
	v_mul_f32_e32 v156, v151, v156
	v_exp_f32_e32 v157, v150
	s_waitcnt lgkmcnt(0)
	v_pk_add_f32 v[148:149], v[148:149], v[154:155]
	ds_bpermute_b32 v151, v102, v149
	ds_bpermute_b32 v150, v102, v148
	v_add_f32_e32 v154, 1.0, v157
	v_rcp_f32_e32 v157, v154
	v_mul_f32_e32 v154, 0xbfb8aa3b, v153
	v_exp_f32_e32 v158, v154
	s_waitcnt lgkmcnt(0)
	v_pk_add_f32 v[150:151], v[148:149], v[150:151]
	ds_bpermute_b32 v155, v103, v151
	ds_bpermute_b32 v154, v103, v150
	v_cvt_pk_bf16_f32 v148, v145, v156
	v_mul_f32_e32 v145, v152, v157
	v_add_f32_e32 v149, 1.0, v158
	v_rcp_f32_e32 v149, v149
	s_waitcnt lgkmcnt(0)
	v_pk_add_f32 v[150:151], v[150:151], v[154:155]
	v_mov_b32_e32 v159, v107
	v_pk_mul_f32 v[150:151], v[150:151], s[4:5] op_sel_hi:[1,0]
	v_mul_f32_e32 v149, v153, v149
	v_fma_f32 v150, -v151, v151, v150
	v_max_f32_e32 v150, 0, v150
	v_add_f32_e32 v150, 0x3727c5ac, v150
	v_mul_f32_e32 v152, 0x4f800000, v150
	v_cmp_gt_f32_e32 vcc, s16, v150
	v_cvt_pk_bf16_f32 v149, v145, v149
	v_sub_f32_e32 v21, v21, v151
	v_sub_f32_e32 v20, v20, v151
	v_cndmask_b32_e32 v150, v150, v152, vcc
	v_sqrt_f32_e32 v152, v150
	v_sub_f32_e32 v23, v23, v151
	v_sub_f32_e32 v22, v22, v151
	v_mov_b32_e32 v158, v108
	v_add_u32_e32 v145, -1, v152
	v_fma_f32 v153, -v145, v152, v150
	v_cmp_ge_f32_e64 s[0:1], 0, v153
	v_add_u32_e32 v153, 1, v152
	v_mov_b32_e32 v156, v109
	v_cndmask_b32_e64 v145, v152, v145, s[0:1]
	v_fma_f32 v152, -v153, v152, v150
	v_cmp_lt_f32_e64 s[0:1], 0, v152
	v_mov_b32_e32 v155, v110
	v_mov_b32_e32 v160, v115
	v_cndmask_b32_e64 v145, v145, v153, s[0:1]
	v_mul_f32_e32 v152, 0x37800000, v145
	v_cndmask_b32_e32 v145, v145, v152, vcc
	v_cmp_class_f32_e32 vcc, v150, v106
	v_mov_b32_e32 v157, v116
	s_nop 0
	v_cndmask_b32_e32 v145, v145, v150, vcc
	v_div_scale_f32 v150, s[0:1], v145, v145, 1.0
	v_rcp_f32_e32 v154, v150
	s_lshl_b64 s[0:1], s[12:13], 11
	v_lshl_add_u64 v[152:153], v[96:97], 0, s[0:1]
	global_store_dwordx4 v[152:153], v[146:149], off
	s_add_i32 s0, s12, 1
	s_ashr_i32 s1, s0, 31
	v_fma_f32 v146, -v150, v154, 1.0
	v_fmac_f32_e32 v154, v146, v154
	v_div_scale_f32 v146, vcc, 1.0, v145, 1.0
	v_mul_f32_e32 v147, v146, v154
	v_fma_f32 v148, -v150, v147, v146
	v_fmac_f32_e32 v147, v148, v154
	v_fma_f32 v146, -v150, v147, v146
	v_div_fmas_f32 v146, v146, v154, v147
	v_div_fixup_f32 v146, v146, v145, 1.0
	v_pk_mul_f32 v[20:21], v[20:21], v[146:147] op_sel_hi:[1,0]
	v_pk_mul_f32 v[22:23], v[22:23], v[146:147] op_sel_hi:[1,0]
	v_pk_fma_f32 v[8:9], v[8:9], v[20:21], v[12:13]
	v_sub_f32_e32 v13, v19, v151
	v_sub_f32_e32 v12, v18, v151
	v_pk_mul_f32 v[12:13], v[12:13], v[146:147] op_sel_hi:[1,0]
	v_pk_fma_f32 v[10:11], v[10:11], v[22:23], v[14:15]
	v_pk_fma_f32 v[6:7], v[2:3], v[12:13], v[6:7]
	v_mul_f32_e32 v2, 0xbfb8aa3b, v8
	v_exp_f32_e32 v12, v2
	v_mul_f32_e32 v2, 0xbfb8aa3b, v9
	v_exp_f32_e32 v13, v2
	v_sub_f32_e32 v15, v17, v151
	v_sub_f32_e32 v14, v16, v151
	v_pk_mul_f32 v[14:15], v[14:15], v[146:147] op_sel_hi:[1,0]
	s_lshl_b64 s[0:1], s[0:1], 11
	v_pk_fma_f32 v[2:3], v[0:1], v[14:15], v[4:5]
	v_add_f32_e32 v0, 1.0, v12
	v_add_f32_e32 v1, 1.0, v13
	v_rcp_f32_e32 v0, v0
	v_rcp_f32_e32 v1, v1
	v_mul_f32_e32 v4, 0xbfb8aa3b, v10
	v_exp_f32_e32 v4, v4
	v_mul_f32_e32 v0, v8, v0
	v_mul_f32_e32 v1, v9, v1
	v_cvt_pk_bf16_f32 v0, v0, v1
	v_add_f32_e32 v1, 1.0, v4
	v_mul_f32_e32 v4, 0xbfb8aa3b, v11
	v_exp_f32_e32 v4, v4
	v_mul_f32_e32 v5, 0xbfb8aa3b, v2
	v_exp_f32_e32 v5, v5
	v_rcp_f32_e32 v1, v1
	v_add_f32_e32 v4, 1.0, v4
	v_rcp_f32_e32 v4, v4
	v_add_f32_e32 v5, 1.0, v5
	v_mul_f32_e32 v8, 0xbfb8aa3b, v3
	v_rcp_f32_e32 v5, v5
	v_exp_f32_e32 v8, v8
	v_mul_f32_e32 v1, v10, v1
	v_mul_f32_e32 v4, v11, v4
	v_cvt_pk_bf16_f32 v1, v1, v4
	v_mul_f32_e32 v2, v2, v5
	v_add_f32_e32 v4, 1.0, v8
	v_mul_f32_e32 v5, 0xbfb8aa3b, v6
	v_mul_f32_e32 v8, 0xbfb8aa3b, v7
	v_exp_f32_e32 v5, v5
	v_exp_f32_e32 v8, v8
	v_rcp_f32_e32 v4, v4
	s_andn2_b64 vcc, exec, s[10:11]
	v_add_f32_e32 v5, 1.0, v5
	v_add_f32_e32 v8, 1.0, v8
	v_rcp_f32_e32 v5, v5
	v_rcp_f32_e32 v8, v8
	v_mul_f32_e32 v3, v3, v4
	v_cvt_pk_bf16_f32 v2, v2, v3
	v_mul_f32_e32 v3, v6, v5
	v_mul_f32_e32 v4, v7, v8
	v_cvt_pk_bf16_f32 v3, v3, v4
	v_lshl_add_u64 v[4:5], v[96:97], 0, s[0:1]
	global_store_dwordx4 v[4:5], v[0:3], off
	v_mov_b32_e32 v152, v111
	v_mov_b32_e32 v149, v112
	v_mov_b32_e32 v147, v113
	v_mov_b32_e32 v23, v114
	v_mov_b32_e32 v154, v117
	v_mov_b32_e32 v151, v118
	v_mov_b32_e32 v148, v119
	v_mov_b32_e32 v22, v120
	v_mov_b32_e32 v19, v121
	v_mov_b32_e32 v15, v122
	v_mov_b32_e32 v153, v123
	v_mov_b32_e32 v150, v124
	v_mov_b32_e32 v146, v125
	v_mov_b32_e32 v21, v126
	v_mov_b32_e32 v17, v127
	v_mov_b32_e32 v14, v128
	v_mov_b32_e32 v10, v129
	v_mov_b32_e32 v7, v130
	v_mov_b32_e32 v145, v131
	v_mov_b32_e32 v20, v132
	v_mov_b32_e32 v18, v133
	v_mov_b32_e32 v16, v134
	v_mov_b32_e32 v12, v135
	v_mov_b32_e32 v8, v136
	v_mov_b32_e32 v3, v137
	v_mov_b32_e32 v2, v138
	v_mov_b32_e32 v13, v139
	v_mov_b32_e32 v11, v140
	v_mov_b32_e32 v9, v141
	v_mov_b32_e32 v6, v142
	v_mov_b32_e32 v5, v143
	v_mov_b32_e32 v4, v144
	s_barrier
	s_cbranch_vccz .LBB0_485
; #define CONV_LOAD(dst, it_) do { const int t0_ = (it_) * 16 + th * 8, tb_ = t0_ & (SEQ - 1); \
;         _Pragma("unroll") for (int r = 0; r < 38; ++r) { const int pos = tb_ - 30 + r; dst[r] = *(const unsigned*)(VC + (size_t)(t0_ - tb_ + (pos < 0 ? 0 : pos)) * CONVC + 2 * cp); } } while (0)
; __device__ __forceinline__ void conv_phase(LAS unsigned char* lds, const bf16_t* VC, const float* cw, const float* cb, const float* lng, const float* lnb, bf16_t* CAT, int tid, int lane, int wave) {
;     ...
;     if ((int)blockIdx.x < T / 16) CONV_LOAD(vn, (int)blockIdx.x);
;     for (int it = blockIdx.x; it < T / 16; it += gridDim.x) {
;         const int t0 = it * 16 + th * 8, tb = t0 & (SEQ - 1);
;         f32x2v av[8];
; #pragma unroll
;         for (int t = 0; t < 8; ++t) av[t] = bias;
;         unsigned vv[38];
; #pragma unroll
;         for (int r = 0; r < 38; ++r) vv[r] = vn[r];
;         if (it + (int)gridDim.x < T / 16) CONV_LOAD(vn, it + (int)gridDim.x);
.LBB0_483:
	s_add_i32 s17, s17, s22
	s_cmpk_gt_i32 s17, 0x7ff
	s_cselect_b64 s[10:11], -1, 0
	s_and_b64 vcc, exec, s[10:11]
	s_cbranch_vccnz .LBB0_482
	s_add_i32 s100, s3, s15
	s_bfe_u32 s98, s100, 0x30004
	s_lshl_b32 s98, s98, 12
	s_lshr_b32 s99, s100, 7
	s_lshl_b32 s99, s99, 4
	s_or_b32 s98, s98, s99
	v_add_u32_e32 v0, s98, v98
	v_and_b32_e32 v1, 0x7f8, v0
	v_and_b32_e32 v142, 0xfffff800, v0
	v_sub_u32_e64 v107, v1, 30 clamp
	v_or_b32_e32 v108, v107, v142
	v_sub_u32_e64 v107, v1, 29 clamp
	v_or_b32_e32 v110, v107, v142
	v_sub_u32_e64 v107, v1, 28 clamp
	v_or_b32_e32 v112, v107, v142
	v_sub_u32_e64 v107, v1, 27 clamp
	v_or_b32_e32 v114, v107, v142
	v_sub_u32_e64 v107, v1, 26 clamp
	v_or_b32_e32 v116, v107, v142
	v_sub_u32_e64 v107, v1, 25 clamp
	v_or_b32_e32 v118, v107, v142
	v_sub_u32_e64 v107, v1, 24 clamp
	v_or_b32_e32 v120, v107, v142
	v_sub_u32_e64 v107, v1, 23 clamp
	v_ashrrev_i32_e32 v109, 31, v108
	v_ashrrev_i32_e32 v111, 31, v110
	v_ashrrev_i32_e32 v113, 31, v112
	v_ashrrev_i32_e32 v115, 31, v114
	v_or_b32_e32 v122, v107, v142
	v_lshlrev_b64 v[108:109], 10, v[108:109]
	v_lshlrev_b64 v[110:111], 10, v[110:111]
	v_lshlrev_b64 v[112:113], 10, v[112:113]
	v_lshlrev_b64 v[114:115], 10, v[114:115]
	v_ashrrev_i32_e32 v117, 31, v116
	v_ashrrev_i32_e32 v119, 31, v118
	v_ashrrev_i32_e32 v121, 31, v120
	v_ashrrev_i32_e32 v123, 31, v122
	v_lshl_add_u64 v[108:109], v[90:91], 0, v[108:109]
	v_lshl_add_u64 v[110:111], v[90:91], 0, v[110:111]
	v_lshl_add_u64 v[112:113], v[90:91], 0, v[112:113]
	v_lshl_add_u64 v[114:115], v[90:91], 0, v[114:115]
	v_lshlrev_b64 v[116:117], 10, v[116:117]
	v_lshlrev_b64 v[118:119], 10, v[118:119]
	v_lshlrev_b64 v[120:121], 10, v[120:121]
	v_lshlrev_b64 v[122:123], 10, v[122:123]
	v_lshl_add_u64 v[116:117], v[90:91], 0, v[116:117]
	v_lshl_add_u64 v[118:119], v[90:91], 0, v[118:119]
	v_lshl_add_u64 v[120:121], v[90:91], 0, v[120:121]
	v_lshl_add_u64 v[122:123], v[90:91], 0, v[122:123]
	global_load_dword v107, v[108:109], off
	s_nop 0
	global_load_dword v108, v[110:111], off
	global_load_dword v109, v[112:113], off
	s_nop 0
	global_load_dword v110, v[114:115], off
	global_load_dword v111, v[116:117], off
	global_load_dword v112, v[118:119], off
	global_load_dword v113, v[120:121], off
	s_nop 0
	global_load_dword v114, v[122:123], off
	v_sub_u32_e64 v115, v1, 22 clamp
	v_or_b32_e32 v116, v115, v142
	v_sub_u32_e64 v115, v1, 21 clamp
	v_or_b32_e32 v118, v115, v142
	v_sub_u32_e64 v115, v1, 20 clamp
	v_or_b32_e32 v120, v115, v142
	v_sub_u32_e64 v115, v1, 19 clamp
	v_or_b32_e32 v122, v115, v142
	v_sub_u32_e64 v115, v1, 18 clamp
	v_or_b32_e32 v124, v115, v142
	v_sub_u32_e64 v115, v1, 17 clamp
	v_or_b32_e32 v126, v115, v142
	v_sub_u32_e64 v115, v1, 16 clamp
	v_or_b32_e32 v128, v115, v142
	v_sub_u32_e64 v115, v1, 15 clamp
	v_ashrrev_i32_e32 v117, 31, v116
	v_ashrrev_i32_e32 v119, 31, v118
	v_ashrrev_i32_e32 v121, 31, v120
	v_ashrrev_i32_e32 v123, 31, v122
	v_or_b32_e32 v130, v115, v142
	v_lshlrev_b64 v[116:117], 10, v[116:117]
	v_lshlrev_b64 v[118:119], 10, v[118:119]
	v_lshlrev_b64 v[120:121], 10, v[120:121]
	v_lshlrev_b64 v[122:123], 10, v[122:123]
	v_ashrrev_i32_e32 v125, 31, v124
	v_ashrrev_i32_e32 v127, 31, v126
	v_ashrrev_i32_e32 v129, 31, v128
	v_ashrrev_i32_e32 v131, 31, v130
	v_lshl_add_u64 v[116:117], v[90:91], 0, v[116:117]
	v_lshl_add_u64 v[118:119], v[90:91], 0, v[118:119]
	v_lshl_add_u64 v[120:121], v[90:91], 0, v[120:121]
	v_lshl_add_u64 v[122:123], v[90:91], 0, v[122:123]
	v_lshlrev_b64 v[124:125], 10, v[124:125]
	v_lshlrev_b64 v[126:127], 10, v[126:127]
	v_lshlrev_b64 v[128:129], 10, v[128:129]
	v_lshlrev_b64 v[130:131], 10, v[130:131]
	v_lshl_add_u64 v[124:125], v[90:91], 0, v[124:125]
	v_lshl_add_u64 v[126:127], v[90:91], 0, v[126:127]
	v_lshl_add_u64 v[128:129], v[90:91], 0, v[128:129]
	v_lshl_add_u64 v[130:131], v[90:91], 0, v[130:131]
	global_load_dword v115, v[116:117], off
	s_nop 0
	global_load_dword v116, v[118:119], off
	global_load_dword v117, v[120:121], off
	s_nop 0
	global_load_dword v118, v[122:123], off
	global_load_dword v119, v[124:125], off
	global_load_dword v120, v[126:127], off
	global_load_dword v121, v[128:129], off
	s_nop 0
	global_load_dword v122, v[130:131], off
	v_sub_u32_e64 v123, v1, 14 clamp
	v_or_b32_e32 v124, v123, v142
	v_sub_u32_e64 v123, v1, 13 clamp
	v_or_b32_e32 v126, v123, v142
	v_sub_u32_e64 v123, v1, 12 clamp
	v_or_b32_e32 v128, v123, v142
	v_sub_u32_e64 v123, v1, 11 clamp
	v_or_b32_e32 v130, v123, v142
	v_sub_u32_e64 v123, v1, 10 clamp
	v_or_b32_e32 v132, v123, v142
; #define CONV_LOAD(dst, it_) do { const int t0_ = (it_) * 16 + th * 8, tb_ = t0_ & (SEQ - 1); \
;         _Pragma("unroll") for (int r = 0; r < 38; ++r) { const int pos = tb_ - 30 + r; dst[r] = *(const unsigned*)(VC + (size_t)(t0_ - tb_ + (pos < 0 ? 0 : pos)) * CONVC + 2 * cp); } } while (0)
; __device__ __forceinline__ void conv_phase(LAS unsigned char* lds, const bf16_t* VC, const float* cw, const float* cb, const float* lng, const float* lnb, bf16_t* CAT, int tid, int lane, int wave) {
;     ...
;     if ((int)blockIdx.x < T / 16) CONV_LOAD(vn, (int)blockIdx.x);
;     for (int it = blockIdx.x; it < T / 16; it += gridDim.x) {
;         const int t0 = it * 16 + th * 8, tb = t0 & (SEQ - 1);
;         f32x2v av[8];
; #pragma unroll
;         for (int t = 0; t < 8; ++t) av[t] = bias;
;         unsigned vv[38];
; #pragma unroll
;         for (int r = 0; r < 38; ++r) vv[r] = vn[r];
;         if (it + (int)gridDim.x < T / 16) CONV_LOAD(vn, it + (int)gridDim.x);
	v_sub_u32_e64 v123, v1, 9 clamp
	v_or_b32_e32 v134, v123, v142
	v_sub_u32_e64 v123, v1, 8 clamp
	v_or_b32_e32 v136, v123, v142
	v_sub_u32_e64 v123, v1, 7 clamp
	v_ashrrev_i32_e32 v125, 31, v124
	v_ashrrev_i32_e32 v127, 31, v126
	v_ashrrev_i32_e32 v129, 31, v128
	v_ashrrev_i32_e32 v131, 31, v130
	v_or_b32_e32 v138, v123, v142
	v_lshlrev_b64 v[124:125], 10, v[124:125]
	v_lshlrev_b64 v[126:127], 10, v[126:127]
	v_lshlrev_b64 v[128:129], 10, v[128:129]
	v_lshlrev_b64 v[130:131], 10, v[130:131]
	v_ashrrev_i32_e32 v133, 31, v132
	v_ashrrev_i32_e32 v135, 31, v134
	v_ashrrev_i32_e32 v137, 31, v136
	v_ashrrev_i32_e32 v139, 31, v138
	v_lshl_add_u64 v[124:125], v[90:91], 0, v[124:125]
	v_lshl_add_u64 v[126:127], v[90:91], 0, v[126:127]
	v_lshl_add_u64 v[128:129], v[90:91], 0, v[128:129]
	v_lshl_add_u64 v[130:131], v[90:91], 0, v[130:131]
	v_lshlrev_b64 v[132:133], 10, v[132:133]
	v_lshlrev_b64 v[134:135], 10, v[134:135]
	v_lshlrev_b64 v[136:137], 10, v[136:137]
	v_lshlrev_b64 v[138:139], 10, v[138:139]
	v_lshl_add_u64 v[132:133], v[90:91], 0, v[132:133]
	v_lshl_add_u64 v[134:135], v[90:91], 0, v[134:135]
	v_lshl_add_u64 v[136:137], v[90:91], 0, v[136:137]
	v_lshl_add_u64 v[138:139], v[90:91], 0, v[138:139]
	global_load_dword v123, v[124:125], off
	s_nop 0
	global_load_dword v124, v[126:127], off
	global_load_dword v125, v[128:129], off
	s_nop 0
	global_load_dword v126, v[130:131], off
	global_load_dword v127, v[132:133], off
	global_load_dword v128, v[134:135], off
	global_load_dword v129, v[136:137], off
	s_nop 0
	global_load_dword v130, v[138:139], off
	v_sub_u32_e64 v131, v1, 6 clamp
	v_or_b32_e32 v132, v131, v142
	v_sub_u32_e64 v131, v1, 5 clamp
	v_or_b32_e32 v134, v131, v142
	v_sub_u32_e64 v131, v1, 4 clamp
	v_or_b32_e32 v136, v131, v142
	v_sub_u32_e64 v131, v1, 3 clamp
	v_or_b32_e32 v138, v131, v142
	v_sub_u32_e64 v131, v1, 2 clamp
	v_sub_u32_e64 v1, v1, 1 clamp
	v_or_b32_e32 v140, v131, v142
	v_or_b32_e32 v142, v1, v142
	v_ashrrev_i32_e32 v133, 31, v132
	v_ashrrev_i32_e32 v135, 31, v134
	v_ashrrev_i32_e32 v137, 31, v136
	v_ashrrev_i32_e32 v139, 31, v138
	v_ashrrev_i32_e32 v141, 31, v140
	v_ashrrev_i32_e32 v143, 31, v142
	v_add_u32_e32 v164, 1, v0
	v_lshlrev_b64 v[132:133], 10, v[132:133]
	v_lshlrev_b64 v[134:135], 10, v[134:135]
	v_lshlrev_b64 v[136:137], 10, v[136:137]
	v_lshlrev_b64 v[138:139], 10, v[138:139]
	v_lshlrev_b64 v[140:141], 10, v[140:141]
	v_lshlrev_b64 v[142:143], 10, v[142:143]
	v_ashrrev_i32_e32 v1, 31, v0
	v_ashrrev_i32_e32 v165, 31, v164
	v_lshl_add_u64 v[132:133], v[90:91], 0, v[132:133]
	v_lshl_add_u64 v[134:135], v[90:91], 0, v[134:135]
	v_lshl_add_u64 v[136:137], v[90:91], 0, v[136:137]
	v_lshl_add_u64 v[138:139], v[90:91], 0, v[138:139]
	v_lshl_add_u64 v[140:141], v[90:91], 0, v[140:141]
	v_lshl_add_u64 v[142:143], v[90:91], 0, v[142:143]
	v_lshlrev_b64 v[162:163], 10, v[0:1]
	v_lshlrev_b64 v[164:165], 10, v[164:165]
	v_lshl_add_u64 v[162:163], v[90:91], 0, v[162:163]
	v_lshl_add_u64 v[164:165], v[90:91], 0, v[164:165]
	global_load_dword v131, v[132:133], off
	s_nop 0
	global_load_dword v132, v[134:135], off
	global_load_dword v133, v[136:137], off
	s_nop 0
	global_load_dword v134, v[138:139], off
	global_load_dword v135, v[140:141], off
	global_load_dword v136, v[142:143], off
	global_load_dword v137, v[162:163], off
	s_nop 0
	global_load_dword v138, v[164:165], off
	v_add_u32_e32 v140, 2, v0
	v_add_u32_e32 v142, 3, v0
	v_ashrrev_i32_e32 v141, 31, v140
	v_ashrrev_i32_e32 v143, 31, v142
	v_add_u32_e32 v162, 4, v0
	v_add_u32_e32 v164, 5, v0
	v_add_u32_e32 v166, 6, v0
	v_add_u32_e32 v0, 7, v0
	v_lshlrev_b64 v[140:141], 10, v[140:141]
	v_lshlrev_b64 v[142:143], 10, v[142:143]
	v_ashrrev_i32_e32 v163, 31, v162
	v_ashrrev_i32_e32 v165, 31, v164
	v_ashrrev_i32_e32 v167, 31, v166
	v_ashrrev_i32_e32 v1, 31, v0
	v_lshl_add_u64 v[140:141], v[90:91], 0, v[140:141]
	v_lshl_add_u64 v[142:143], v[90:91], 0, v[142:143]
	v_lshlrev_b64 v[162:163], 10, v[162:163]
	v_lshlrev_b64 v[164:165], 10, v[164:165]
	v_lshlrev_b64 v[166:167], 10, v[166:167]
	v_lshlrev_b64 v[0:1], 10, v[0:1]
	v_lshl_add_u64 v[162:163], v[90:91], 0, v[162:163]
	v_lshl_add_u64 v[164:165], v[90:91], 0, v[164:165]
	v_lshl_add_u64 v[166:167], v[90:91], 0, v[166:167]
	v_lshl_add_u64 v[0:1], v[90:91], 0, v[0:1]
	global_load_dword v139, v[140:141], off
	s_nop 0
	global_load_dword v140, v[142:143], off
	global_load_dword v141, v[162:163], off
	s_nop 0
	global_load_dword v142, v[164:165], off
	global_load_dword v143, v[166:167], off
	global_load_dword v144, v[0:1], off
	s_branch .LBB0_482

; #define LAS __attribute__((address_space(3)))
; __device__ __forceinline__ void ssm_bu_tile(const SsmOps& S, bf16x8 uh, LAS float* tile, int lane) {
;     const int fr = lane & 15, fq = lane >> 4;
;     if (fq >= 2) uh = (bf16x8){0, 0, 0, 0, 0, 0, 0, 0};
; #pragma unroll
;     for (int nb = 0; nb < 8; ++nb) { f32x4 acc = {0.f, 0.f, 0.f, 0.f};
;         acc = __builtin_amdgcn_mfma_f32_16x16x32_bf16(S.bh[nb], uh, acc, 0, 0, 0);
;         *(LAS f32x4*)(tile + fr * TSTR + 16 * nb + 4 * fq) = acc; }
;     asm volatile("s_waitcnt lgkmcnt(0)" ::: "memory");
; }
; __device__ __forceinline__ void ssm_pass1(LAS unsigned char* lds, const bf16_t* US, float* SST, const float* ABAR, const bf16_t* BBH, const bf16_t* BBL, int gw, int NGW, int lane, int wave) {
;     LAS float* tile = (LAS float*)(lds + 32768 + wave * (16 * TSTR * 4));
;     for (int idx = gw; idx < NB * NG * 7; idx += NGW) {
;         const int c = idx % 7, bg = idx / 7, b = bg >> 5, g = bg & 31;
;         SsmOps S; ssm_ops_load(S, ABAR, BBH, BBL, g, lane);
;         float xr = 0.f, xi = 0.f; const int tokc = b * SEQ + c * 256;
;         bf16x8 uh; ssm_u_load(uh, US, tokc, g, lane);
;         for (int grp = 0; grp < 16; ++grp) {
;             ssm_bu_tile(S, uh, tile, lane);
;             if (grp < 15) ssm_u_load(uh, US, tokc + (grp + 1) * 16, g, lane);
.LBB0_487:
	s_lshr_b32 s16, s3, 9
	s_bfe_u32 s14, s3, 0x30003
	s_lshl_b32 s14, s14, 1
	s_bfe_u32 s12, s3, 0x10008
	s_or_b32 s14, s14, s12
	s_bfe_u32 s12, s3, 0x20006
	s_lshl_b32 s12, s12, 3
	s_and_b32 s15, s3, 7
	s_or_b32 s12, s12, s15
	s_lshl_b32 s14, s14, 5
	s_or_b32 s14, s14, s12
	s_lshl_b32 s17, s14, 6
	s_and_b32 s12, s14, 31
	s_and_b32 s15, s17, 0xfffff800
	s_lshl_b32 s17, s16, 8
	v_lshl_or_b32 v0, s12, 12, v52
	v_lshl_or_b32 v1, s12, 9, v53
	s_add_i32 s17, s15, s17
	global_load_dwordx2 v[40:41], v1, s[0:1]
	global_load_dwordx4 v[4:7], v0, s[10:11]
	global_load_dwordx4 v[8:11], v0, s[10:11] offset:512
	global_load_dwordx4 v[12:15], v0, s[10:11] offset:1024
	global_load_dwordx4 v[16:19], v0, s[10:11] offset:1536
	global_load_dwordx4 v[20:23], v0, s[10:11] offset:2048
	global_load_dwordx4 v[24:27], v0, s[10:11] offset:2560
	global_load_dwordx4 v[56:59], v0, s[10:11] offset:3072
	global_load_dwordx4 v[60:63], v0, s[10:11] offset:3584
	v_or_b32_e32 v0, s17, v48
	v_ashrrev_i32_e32 v1, 31, v0
	v_lshlrev_b64 v[0:1], 10, v[0:1]
	s_lshl_b32 s12, s12, 5
	v_lshl_add_u64 v[0:1], s[46:47], 0, v[0:1]
	v_lshl_add_u64 v[0:1], v[0:1], 0, s[12:13]
	v_lshl_add_u64 v[0:1], v[0:1], 0, v[36:37]
	global_load_dwordx4 v[0:3], v[0:1], off
	v_lshl_add_u64 v[42:43], v[38:39], 0, s[12:13]
	v_or_b32_e32 v55, s17, v51
	s_mov_b32 s12, 0
	v_mov_b32_e32 v46, 0
	v_mov_b32_e32 v47, v37
	s_waitcnt vmcnt(0)
	v_pk_mov_b32 v[44:45], v[40:41], v[40:41] op_sel:[1,0]
	v_cndmask_b32_e32 v7, 0, v7, vcc
	v_cndmask_b32_e32 v6, 0, v6, vcc
	v_cndmask_b32_e32 v5, 0, v5, vcc
	v_cndmask_b32_e32 v4, 0, v4, vcc
	v_cndmask_b32_e32 v11, 0, v11, vcc
	v_cndmask_b32_e32 v10, 0, v10, vcc
	v_cndmask_b32_e32 v9, 0, v9, vcc
	v_cndmask_b32_e32 v8, 0, v8, vcc
	v_cndmask_b32_e32 v15, 0, v15, vcc
	v_cndmask_b32_e32 v14, 0, v14, vcc
	v_cndmask_b32_e32 v13, 0, v13, vcc
	v_cndmask_b32_e32 v12, 0, v12, vcc
	v_cndmask_b32_e32 v19, 0, v19, vcc
	v_cndmask_b32_e32 v18, 0, v18, vcc
	v_cndmask_b32_e32 v17, 0, v17, vcc
	v_cndmask_b32_e32 v16, 0, v16, vcc
	v_cndmask_b32_e32 v31, 0, v23, vcc
	v_cndmask_b32_e32 v30, 0, v22, vcc
	v_cndmask_b32_e32 v29, 0, v21, vcc
	v_cndmask_b32_e32 v28, 0, v20, vcc
	v_cndmask_b32_e32 v35, 0, v27, vcc
	v_cndmask_b32_e32 v34, 0, v26, vcc
	v_cndmask_b32_e32 v33, 0, v25, vcc
	v_cndmask_b32_e32 v32, 0, v24, vcc
	v_cndmask_b32_e32 v27, 0, v59, vcc
	v_cndmask_b32_e32 v26, 0, v58, vcc
	v_cndmask_b32_e32 v25, 0, v57, vcc
	v_cndmask_b32_e32 v24, 0, v56, vcc
	v_cndmask_b32_e32 v23, 0, v63, vcc
	v_cndmask_b32_e32 v22, 0, v62, vcc
	v_cndmask_b32_e32 v21, 0, v61, vcc
	v_cndmask_b32_e32 v20, 0, v60, vcc
	v_readlane_b32 s98, v249, 18
	s_mov_b32 s100, 0x4000
	s_mov_b32 s101, 0
	s_mov_b32 s12, 0
	s_mul_i32 s98, s98, 0x2800
	s_add_i32 s98, s98, 0x8000
	v_lshrrev_b32_e32 v109, 4, v196
	v_mul_u32_u24_e32 v144, 0x50, v48
	v_lshl_add_u32 v144, v109, 4, v144
	v_add_u32_e32 v144, s98, v144
	v_mul_u32_u24_e32 v145, 0x50, v196
	v_add_u32_e32 v145, s98, v145
	v_xor_b32_e32 v77, 0x80000000, v41
	v_mov_b32_e32 v100, 0
	v_mov_b32_e32 v76, 0
	v_lshlrev_b32_e32 v112, 10, v55
	v_mov_b32_e32 v113, 0
	v_lshl_add_u64 v[148:149], v[42:43], 0, v[112:113]
	v_cndmask_b32_e64 v235, v3, 0, s[4:5]
	v_cndmask_b32_e64 v234, v2, 0, s[4:5]
	v_cndmask_b32_e64 v233, v1, 0, s[4:5]
	v_cndmask_b32_e64 v232, v0, 0, s[4:5]
	global_load_dwordx4 v[0:3], v[148:149], off
	v_lshl_add_u64 v[148:149], v[148:149], 0, s[100:101]
	v_mfma_f32_16x16x32_bf16 v[160:163], v[232:235], v[4:7], 0
	v_mfma_f32_16x16x32_bf16 v[164:167], v[232:235], v[8:11], 0
	v_mfma_f32_16x16x32_bf16 v[168:171], v[232:235], v[12:15], 0
	v_mfma_f32_16x16x32_bf16 v[172:175], v[232:235], v[16:19], 0
	v_mfma_f32_16x16x32_bf16 v[176:179], v[232:235], v[28:31], 0
	v_mfma_f32_16x16x32_bf16 v[180:183], v[232:235], v[32:35], 0
	v_mfma_f32_16x16x32_bf16 v[184:187], v[232:235], v[24:27], 0
	v_mfma_f32_16x16x32_bf16 v[188:191], v[232:235], v[20:23], 0
	s_nop 0
	ds_write_b128 v144, v[160:163]
	ds_write_b128 v144, v[164:167] offset:1280
	ds_write_b128 v144, v[168:171] offset:2560
	ds_write_b128 v144, v[172:175] offset:3840
	ds_write_b128 v144, v[176:179] offset:5120
	ds_write_b128 v144, v[180:183] offset:6400
	ds_write_b128 v144, v[184:187] offset:7680
	ds_write_b128 v144, v[188:191] offset:8960

; __device__ __forceinline__ unsigned xb_ld(unsigned* p)              { return __hip_atomic_load(p, __ATOMIC_RELAXED, __HIP_MEMORY_SCOPE_AGENT); }
; __device__ __forceinline__ unsigned xb_add(unsigned* p, unsigned v) { return __hip_atomic_fetch_add(p, v, __ATOMIC_RELAXED, __HIP_MEMORY_SCOPE_AGENT); }
; #define XB_SPIN(cond, bar) do { unsigned _sp = 0; while (cond) { __builtin_amdgcn_s_sleep(1); \
;     if ((++_sp & 255u) == 0u) { if (xb_ld(&(bar)[XB_TMO])) break; if (_sp > XB_SPIN_CAP) { atomicAdd(&(bar)[XB_TMO], 1u); break; } } } } while (0)
; __device__ __forceinline__ void xcd_barrier(const XcdBarrier& b) {
;     ...
;         const unsigned old = xb_add(&bar[XB_XSUB(b.x)], 1u);
;         const unsigned gen = old / nloc;
;         if (old + 1u == (gen + 1u) * nloc) {
;             __builtin_amdgcn_fence(__ATOMIC_RELEASE, "agent");
;             asm volatile("s_waitcnt vmcnt(0)" ::: "memory");
;             const unsigned og = xb_add(&bar[XB_TOP], 1u);
;             const unsigned tg = og / nx;
;             if (og + 1u == (tg + 1u) * nx) xb_add(&bar[XB_TOPGEN], 1u);
;             else XB_SPIN(xb_ld(&bar[XB_TOPGEN]) == tg, bar);
;             __builtin_amdgcn_fence(__ATOMIC_ACQUIRE, "agent");
;             xb_add(&bar[XB_XGEN(b.x)], 1u);
;             asm volatile("s_waitcnt vmcnt(0)" ::: "memory");
.LBB0_523:
	s_andn2_saveexec_b64 s[10:11], s[10:11]
	s_cbranch_execz .LBB0_543
	s_mov_b64 s[10:11], exec
	v_readlane_b32 s3, v249, 48
	s_nop 3
	s_cmp_lg_u32 s3, 0
	s_cbranch_scc1 .LBB0_540
	buffer_wbl2 sc1
	s_waitcnt lgkmcnt(0)
	s_waitcnt vmcnt(0)
	v_mbcnt_lo_u32_b32 v1, s10, 0
	v_mbcnt_hi_u32_b32 v1, s11, v1
	v_cmp_eq_u32_e32 vcc, 0, v1
	s_and_saveexec_b64 s[12:13], vcc
	s_cbranch_execz .LBB0_526
	s_bcnt1_i32_b64 s3, s[10:11]
	v_mov_b32_e32 v2, 0x183000
	v_mov_b32_e32 v3, s3
	global_atomic_add v2, v2, v3, s[28:29] offset:1024 sc0

; __device__ __forceinline__ void ssm_pass2(LAS unsigned char* lds, const bf16_t* US, const float* SST, bf16_t* YB, const float* ABAR, const bf16_t* BBH, const bf16_t* BBL, const bf16_t* CMH, const bf16_t* CML, const float* dco, int gw, int NGW, int lane, int wave) {
;     ...
;     for (int idx = gw; idx < NB * NG * 8; idx += NGW) {
;         const int c = idx & 7, bg = idx >> 3, b = bg >> 5, g = bg & 31;
;         SsmOps S; ssm_ops_load(S, ABAR, BBH, BBL, g, lane);
;         bf16x8 ch[4];
; #pragma unroll
;         for (int ks = 0; ks < 4; ++ks) { const size_t o = (size_t)(g * 16 + fr) * 128 + ks * 32 + fq * 8; ch[ks] = *(const bf16x8*)(CMH + o); }
;         const float dh = dco[g * 16 + fr];
;         float pr = S.ar, pi = S.ai;
; #pragma unroll
;         for (int s = 0; s < 8; ++s) { const float nr = pr * pr - pi * pi, ni = 2.f * pr * pi; pr = nr; pi = ni; }
;         float xr = 0.f, xi = 0.f;
;         { float sr[7], sm[7];
; #pragma unroll
;           for (int cc = 0; cc < 7; ++cc) { const float* si = SST + ((size_t)bg * 8 + (cc < c ? cc : 0)) * 128; sr[cc] = si[lane]; sm[cc] = si[64 + lane]; }
; #pragma unroll
;           for (int cc = 0; cc < 7; ++cc) if (cc < c) { const float nr = pr * xr - pi * xi + sr[cc], ni = pr * xi + pi * xr + sm[cc]; xr = nr; xi = ni; } }
;         const int tokc = b * SEQ + c * 256;
;         bf16x8 uh; ssm_u_load(uh, US, tokc, g, lane);
;         for (int grp = 0; grp < 16; ++grp) { const int tok = tokc + grp * 16;
;             ssm_bu_tile(S, uh, tile, lane);
;             if (grp < 15) ssm_u_load(uh, US, tok + 16, g, lane);
.LBB0_547:
	s_ashr_i32 s72, s70, 3
	s_and_b32 s20, s72, 31
	s_bfe_u32 s20, s72, 0x50003
	s_and_b32 s21, s72, 7
	s_lshl_b32 s21, s21, 1
	s_lshr_b32 s72, s72, 8
	s_or_b32 s21, s21, s72
	s_lshl_b32 s72, s21, 5
	s_or_b32 s72, s72, s20
	s_lshl_b32 s21, s20, 11
	v_or_b32_e32 v0, s21, v115
	v_lshlrev_b32_e32 v0, 1, v0
	v_or_b32_e32 v1, s21, v116
	global_load_dwordx4 v[16:19], v0, s[52:53]
	global_load_dwordx4 v[20:23], v0, s[52:53] offset:512
	global_load_dwordx4 v[24:27], v0, s[52:53] offset:1024
	global_load_dwordx4 v[28:31], v0, s[52:53] offset:1536
	global_load_dwordx4 v[32:35], v0, s[52:53] offset:2048
	global_load_dwordx4 v[36:39], v0, s[52:53] offset:2560
	global_load_dwordx4 v[40:43], v0, s[52:53] offset:3072
	global_load_dwordx4 v[44:47], v0, s[52:53] offset:3584
	v_lshl_or_b32 v0, s20, 9, v122
	v_lshlrev_b32_e32 v1, 1, v1
	global_load_dwordx2 v[90:91], v0, s[50:51]
	global_load_dwordx4 v[12:15], v1, s[54:55]
	global_load_dwordx4 v[8:11], v1, s[54:55] offset:64
	global_load_dwordx4 v[4:7], v1, s[54:55] offset:128
	s_nop 0
	global_load_dwordx4 v[0:3], v1, s[54:55] offset:192
	s_lshl_b32 s20, s20, 4
	v_or_b32_e32 v48, s20, v114
	s_ashr_i32 s73, s72, 31
	v_lshlrev_b32_e32 v48, 2, v48
	s_lshl_b64 s[72:73], s[72:73], 12
	global_load_dword v124, v48, s[38:39]
	v_lshl_add_u64 v[48:49], v[82:83], 0, s[72:73]
	s_mov_b32 s61, s57
	v_lshl_add_u64 v[52:53], v[48:49], 0, s[56:57]
	s_mov_b32 s59, s57
	v_lshl_add_u64 v[56:57], v[48:49], 0, s[60:61]
	s_mov_b32 s63, s57
	v_lshl_add_u64 v[54:55], v[48:49], 0, s[58:59]
	v_lshl_add_u64 v[58:59], v[48:49], 0, s[62:63]
	global_load_dword v50, v[52:53], off
	global_load_dword v64, v[52:53], off offset:256
	global_load_dword v62, v[54:55], off
	global_load_dword v63, v[54:55], off offset:256
	global_load_dword v60, v[56:57], off
	global_load_dword v61, v[56:57], off offset:256
	s_nop 0
	global_load_dword v56, v[58:59], off
	global_load_dword v57, v[58:59], off offset:256
	s_mov_b32 s65, s57
	v_lshl_add_u64 v[52:53], v[48:49], 0, s[64:65]
	s_mov_b32 s67, s57
	v_lshl_add_u64 v[66:67], v[48:49], 0, s[66:67]
	global_load_dword v58, v[52:53], off
	global_load_dword v59, v[52:53], off offset:256
	global_load_dword v54, v[66:67], off
	global_load_dword v55, v[66:67], off offset:256
	v_mov_b32_e32 v52, 0
	s_andn2_b64 vcc, exec, s[34:35]
	s_waitcnt vmcnt(0)
	v_pk_mul_f32 v[66:67], v[90:91], v[90:91]
	v_add_f32_e32 v51, v90, v90
	v_sub_f32_e32 v53, v66, v67
	v_mul_f32_e32 v51, v91, v51
	v_mul_f32_e32 v65, v53, v53
	v_add_f32_e32 v53, v53, v53
	v_fma_f32 v65, -v51, v51, v65
	v_mul_f32_e32 v51, v51, v53
	v_mul_f32_e32 v53, v51, v51
	v_add_f32_e32 v66, v65, v65
	v_fma_f32 v53, v65, v65, -v53
	v_mul_f32_e32 v51, v51, v66
	v_mul_f32_e32 v65, v51, v51
	v_add_f32_e32 v66, v53, v53
	v_fma_f32 v53, v53, v53, -v65
	v_mul_f32_e32 v51, v51, v66
	v_mul_f32_e32 v65, v51, v51
	v_add_f32_e32 v66, v53, v53
	v_fma_f32 v53, v53, v53, -v65
	v_mul_f32_e32 v51, v51, v66
	v_mul_f32_e32 v65, v51, v51
	v_add_f32_e32 v66, v53, v53
	v_fma_f32 v53, v53, v53, -v65
	v_mul_f32_e32 v51, v51, v66
	v_mul_f32_e32 v65, v51, v51
	v_add_f32_e32 v66, v53, v53
	v_fma_f32 v53, v53, v53, -v65
	v_mul_f32_e32 v51, v51, v66
	v_mul_f32_e32 v65, v51, v51
	v_add_f32_e32 v66, v53, v53
	v_fma_f32 v65, v53, v53, -v65
	v_mul_f32_e32 v66, v51, v66
	v_mov_b32_e32 v53, 0
	s_cbranch_vccnz .LBB0_549
	global_load_dword v52, v[48:49], off offset:256
	global_load_dword v53, v[48:49], off
	v_mul_f32_e32 v48, 0, v65
	v_mul_f32_e32 v49, 0, v66
	v_add_f32_e32 v48, v48, v49
	v_fma_f32 v49, v65, 0, -v49
	s_waitcnt vmcnt(0)
	v_pk_add_f32 v[52:53], v[48:49], v[52:53]
.LBB0_549:
	s_and_b32 s21, s68, 0xfffff800
	v_or_b32_e32 v125, s21, v120
	v_or_b32_e32 v126, s21, v121
	s_bfe_u32 s21, s70, 0x30003
	s_lshl_b32 s21, s21, 1
	s_lshr_b32 s59, s70, 11
	s_or_b32 s21, s21, s59
	s_lshl_b32 s21, s21, 11
	v_mul_f32_e32 v48, v66, v52
	v_fma_f32 v48, v65, v53, -v48
	s_or_b32 s59, s21, s3
	v_add_f32_e32 v68, v50, v48
	v_or_b32_e32 v48, s59, v114
	v_ashrrev_i32_e32 v49, 31, v48
	v_lshlrev_b64 v[48:49], 10, v[48:49]
	v_lshl_add_u64 v[48:49], s[46:47], 0, v[48:49]
	s_lshl_b32 s20, s20, 1
	s_mov_b32 s21, s57
	v_lshl_add_u64 v[48:49], v[48:49], 0, s[20:21]
	v_lshl_add_u64 v[48:49], v[48:49], 0, v[80:81]
	global_load_dwordx4 v[48:51], v[48:49], off
	v_mul_f32_e32 v67, v66, v53
	v_fmac_f32_e32 v67, v65, v52
	v_add_f32_e32 v64, v64, v67
	v_cndmask_b32_e64 v52, v52, v64, s[8:9]
	v_cndmask_b32_e64 v53, v53, v68, s[8:9]
	v_mul_f32_e32 v64, v66, v53
	v_mul_f32_e32 v67, v66, v52
	v_fmac_f32_e32 v64, v65, v52
	v_fma_f32 v67, v65, v53, -v67
	v_add_f32_e32 v62, v62, v67
	v_add_f32_e32 v63, v63, v64
	v_cndmask_b32_e64 v52, v52, v63, s[10:11]
	v_cndmask_b32_e64 v53, v53, v62, s[10:11]
	v_mul_f32_e32 v62, v66, v53
	v_mul_f32_e32 v63, v66, v52
	v_fmac_f32_e32 v62, v65, v52
	v_fma_f32 v63, v65, v53, -v63
	v_add_f32_e32 v60, v60, v63
	v_add_f32_e32 v61, v61, v62
	v_cndmask_b32_e64 v52, v52, v61, s[12:13]
	v_cndmask_b32_e64 v53, v53, v60, s[12:13]
	v_mul_f32_e32 v60, v66, v53
	v_mul_f32_e32 v61, v66, v52
	v_fmac_f32_e32 v60, v65, v52
	v_fma_f32 v61, v65, v53, -v61
	v_add_f32_e32 v56, v56, v61
	v_add_f32_e32 v57, v57, v60
	v_cndmask_b32_e64 v52, v52, v57, s[14:15]
	v_cndmask_b32_e64 v53, v53, v56, s[14:15]
	v_mul_f32_e32 v56, v66, v53
	v_mul_f32_e32 v57, v66, v52
	v_fmac_f32_e32 v56, v65, v52
	v_fma_f32 v57, v65, v53, -v57
	v_add_f32_e32 v57, v58, v57
	v_add_f32_e32 v56, v59, v56
	v_cndmask_b32_e64 v52, v52, v56, s[16:17]
	v_cndmask_b32_e64 v53, v53, v57, s[16:17]
	v_mul_f32_e32 v56, v66, v53
	v_mul_f32_e32 v57, v66, v52
	v_fmac_f32_e32 v56, v65, v52
	v_fma_f32 v57, v65, v53, -v57
	v_add_f32_e32 v54, v54, v57
; __device__ __forceinline__ void ssm_bu_tile(const SsmOps& S, bf16x8 uh, LAS float* tile, int lane) {
;     const int fr = lane & 15, fq = lane >> 4;
;     if (fq >= 2) uh = (bf16x8){0, 0, 0, 0, 0, 0, 0, 0};
; #pragma unroll
;     for (int nb = 0; nb < 8; ++nb) { f32x4 acc = {0.f, 0.f, 0.f, 0.f};
;         acc = __builtin_amdgcn_mfma_f32_16x16x32_bf16(S.bh[nb], uh, acc, 0, 0, 0);
;         *(LAS f32x4*)(tile + fr * TSTR + 16 * nb + 4 * fq) = acc; }
;     asm volatile("s_waitcnt lgkmcnt(0)" ::: "memory");
; }
; __device__ __forceinline__ void ssm_pass1(LAS unsigned char* lds, const bf16_t* US, float* SST, const float* ABAR, const bf16_t* BBH, const bf16_t* BBL, int gw, int NGW, int lane, int wave) {
;     LAS float* tile = (LAS float*)(lds + 32768 + wave * (16 * TSTR * 4));
;     for (int idx = gw; idx < NB * NG * 7; idx += NGW) {
;         const int c = idx % 7, bg = idx / 7, b = bg >> 5, g = bg & 31;
;         SsmOps S; ssm_ops_load(S, ABAR, BBH, BBL, g, lane);
;         float xr = 0.f, xi = 0.f; const int tokc = b * SEQ + c * 256;
;         bf16x8 uh; ssm_u_load(uh, US, tokc, g, lane);
;         for (int grp = 0; grp < 16; ++grp) {
;             ssm_bu_tile(S, uh, tile, lane);
;             if (grp < 15) ssm_u_load(uh, US, tokc + (grp + 1) * 16, g, lane);
;             float br[16], bi[16];
; #pragma unroll
;             for (int t = 0; t < 16; ++t) { br[t] = tile[t * TSTR + lane]; bi[t] = tile[t * TSTR + 64 + lane]; }
;             asm volatile("s_waitcnt lgkmcnt(0)" ::: "memory");
; #pragma unroll
;             for (int t = 0; t < 16; ++t) { const float nr = S.ar * xr - S.ai * xi + br[t], ni = S.ar * xi + S.ai * xr + bi[t]; xr = nr; xi = ni; }
;         }
;         float* so = SST + ((size_t)bg * 8 + c) * 128; so[lane] = xr; so[64 + lane] = xi;
;     }
; }
; __device__ __forceinline__ void ssm_pass2(LAS unsigned char* lds, const bf16_t* US, const float* SST, bf16_t* YB, const float* ABAR, const bf16_t* BBH, const bf16_t* BBL, const bf16_t* CMH, const bf16_t* CML, const float* dco, int gw, int NGW, int lane, int wave) {
;     LAS float* tile = (LAS float*)(lds + wave * (16 * TSTR * 4));
;     const int fr = lane & 15, fq = lane >> 4;
;     for (int idx = gw; idx < NB * NG * 8; idx += NGW) {
;         const int c = idx & 7, bg = idx >> 3, b = bg >> 5, g = bg & 31;
;         SsmOps S; ssm_ops_load(S, ABAR, BBH, BBL, g, lane);
;         bf16x8 ch[4];
	v_add_f32_e32 v55, v55, v56
	v_pk_mov_b32 v[94:95], v[90:91], v[90:91] op_sel:[1,0]
	v_cndmask_b32_e64 v76, v52, v55, s[18:19]
	v_cndmask_b32_e64 v100, v53, v54, s[18:19]
	v_cndmask_b32_e64 v19, 0, v19, s[4:5]
	v_cndmask_b32_e64 v18, 0, v18, s[4:5]
	v_cndmask_b32_e64 v17, 0, v17, s[4:5]
	v_cndmask_b32_e64 v16, 0, v16, s[4:5]
	v_cndmask_b32_e64 v23, 0, v23, s[4:5]
	v_cndmask_b32_e64 v22, 0, v22, s[4:5]
	v_cndmask_b32_e64 v21, 0, v21, s[4:5]
	v_cndmask_b32_e64 v20, 0, v20, s[4:5]
	v_cndmask_b32_e64 v27, 0, v27, s[4:5]
	v_cndmask_b32_e64 v26, 0, v26, s[4:5]
	v_cndmask_b32_e64 v25, 0, v25, s[4:5]
	v_cndmask_b32_e64 v24, 0, v24, s[4:5]
	v_cndmask_b32_e64 v31, 0, v31, s[4:5]
	v_cndmask_b32_e64 v30, 0, v30, s[4:5]
	v_cndmask_b32_e64 v29, 0, v29, s[4:5]
	v_cndmask_b32_e64 v28, 0, v28, s[4:5]
	v_cndmask_b32_e64 v35, 0, v35, s[4:5]
	v_cndmask_b32_e64 v34, 0, v34, s[4:5]
	v_cndmask_b32_e64 v33, 0, v33, s[4:5]
	v_cndmask_b32_e64 v32, 0, v32, s[4:5]
	v_cndmask_b32_e64 v39, 0, v39, s[4:5]
	v_cndmask_b32_e64 v38, 0, v38, s[4:5]
	v_cndmask_b32_e64 v37, 0, v37, s[4:5]
	v_cndmask_b32_e64 v36, 0, v36, s[4:5]
	v_cndmask_b32_e64 v43, 0, v43, s[4:5]
	v_cndmask_b32_e64 v42, 0, v42, s[4:5]
	v_cndmask_b32_e64 v41, 0, v41, s[4:5]
	v_cndmask_b32_e64 v40, 0, v40, s[4:5]
	v_cndmask_b32_e64 v47, 0, v47, s[4:5]
	v_cndmask_b32_e64 v46, 0, v46, s[4:5]
	v_cndmask_b32_e64 v45, 0, v45, s[4:5]
	v_cndmask_b32_e64 v44, 0, v44, s[4:5]
	v_lshl_add_u64 v[98:99], v[84:85], 0, s[20:21]
	v_lshl_add_u64 v[96:97], v[86:87], 0, s[20:21]
	v_lshl_add_u64 v[92:93], v[88:89], 0, s[20:21]
	v_readlane_b32 s98, v249, 18
	s_mov_b32 s100, 0x4000
	s_mov_b32 s101, 0
	s_lshl_b32 s99, s20, 7
	s_mul_i32 s98, s98, 0x3a00
	v_lshrrev_b32_e32 v109, 4, v196
	v_mul_u32_u24_e32 v144, 0x50, v114
	v_lshl_add_u32 v144, v109, 4, v144
	v_add_u32_e32 v144, s98, v144
	v_mul_u32_u24_e32 v145, 0x50, v196
	v_add_u32_e32 v145, s98, v145
	v_lshl_add_u32 v146, v196, 2, s98
	v_add_u32_e32 v146, 0x2800, v146
	v_mul_u32_u24_e32 v147, 0x120, v114
	v_lshl_add_u32 v147, v109, 4, v147
	v_add_u32_e32 v147, s98, v147
	v_add_u32_e32 v147, 0x2800, v147
	v_xor_b32_e32 v77, 0x80000000, v91
	v_add_u32_e32 v108, s59, v114
	v_add_u32_e32 v108, 16, v108
	v_lshlrev_b32_e32 v108, 10, v108
	v_mov_b32_e32 v111, 0
	v_mov_b32_e32 v112, v108
	v_mov_b32_e32 v113, v111
	v_lshl_add_u64 v[148:149], v[98:99], 0, v[112:113]
	global_load_dwordx4 v[56:59], v[148:149], off
	v_lshl_add_u64 v[148:149], v[148:149], 0, s[100:101]
	v_lshlrev_b32_e32 v110, 8, v114
	v_lshl_add_u32 v110, v109, 3, v110
	v_add_u32_e32 v110, s99, v110
	global_load_dwordx2 v[230:231], v110, s[54:55] offset:0
	global_load_dwordx2 v[232:233], v110, s[54:55] offset:128
	global_load_dwordx2 v[234:235], v110, s[54:55] offset:32
	global_load_dwordx2 v[236:237], v110, s[54:55] offset:160
	global_load_dwordx2 v[238:239], v110, s[54:55] offset:64
	global_load_dwordx2 v[240:241], v110, s[54:55] offset:192
	global_load_dwordx2 v[242:243], v110, s[54:55] offset:96
	global_load_dwordx2 v[244:245], v110, s[54:55] offset:224
	v_mov_b32_e32 v109, 0
	v_lshrrev_b32_e32 v108, 4, v196
	v_lshl_add_u32 v108, v108, 2, s59
	v_and_b32_e32 v111, 3, v114
	v_add_u32_e32 v108, v108, v111
	v_lshlrev_b32_e32 v108, 10, v108
	v_lshrrev_b32_e32 v111, 2, v114
	v_lshl_add_u32 v108, v111, 3, v108
	v_add_u32_e32 v108, s20, v108
	v_lshl_add_u64 v[150:151], s[0:1], 0, v[108:109]
	s_mov_b32 s99, 0xffff0000
	s_mov_b32 s20, 0
	s_waitcnt vmcnt(0)
	v_and_b32_e32 v101, 0xffff, v230
	v_lshrrev_b32_e32 v102, 16, v230
	v_and_b32_e32 v103, 0xffff, v231
	v_lshrrev_b32_e32 v104, 16, v231
	v_lshl_or_b32 v214, v232, 16, v101
	v_and_or_b32 v215, v232, s99, v102
	v_lshl_or_b32 v216, v233, 16, v103
	v_and_or_b32 v217, v233, s99, v104
	v_and_b32_e32 v101, 0xffff, v234
	v_lshrrev_b32_e32 v102, 16, v234
	v_and_b32_e32 v103, 0xffff, v235
	v_lshrrev_b32_e32 v104, 16, v235
	v_lshl_or_b32 v218, v236, 16, v101
	v_and_or_b32 v219, v236, s99, v102
	v_lshl_or_b32 v220, v237, 16, v103
	v_and_or_b32 v221, v237, s99, v104
	v_and_b32_e32 v101, 0xffff, v238
	v_lshrrev_b32_e32 v102, 16, v238
	v_and_b32_e32 v103, 0xffff, v239
	v_lshrrev_b32_e32 v104, 16, v239
	v_lshl_or_b32 v222, v240, 16, v101
	v_and_or_b32 v223, v240, s99, v102
	v_lshl_or_b32 v224, v241, 16, v103
	v_and_or_b32 v225, v241, s99, v104
	v_and_b32_e32 v101, 0xffff, v242
	v_lshrrev_b32_e32 v102, 16, v242
	v_and_b32_e32 v103, 0xffff, v243
	v_lshrrev_b32_e32 v104, 16, v243
	v_lshl_or_b32 v226, v244, 16, v101
	v_and_or_b32 v227, v244, s99, v102
	v_lshl_or_b32 v228, v245, 16, v103
	v_and_or_b32 v229, v245, s99, v104
	s_mov_b32 s98, 0xaaaaaaaa
	s_mov_b32 s99, 0xaaaaaaaa
	s_mov_b32 vcc_lo, 0xcccccccc
	s_mov_b32 vcc_hi, 0xcccccccc
	v_cndmask_b32_e64 v55, v51, 0, s[6:7]
	v_cndmask_b32_e64 v54, v50, 0, s[6:7]
	v_cndmask_b32_e64 v53, v49, 0, s[6:7]
	v_cndmask_b32_e64 v52, v48, 0, s[6:7]
	v_mov_b32_e32 v48, v56
	v_mov_b32_e32 v49, v57
	v_mov_b32_e32 v50, v58
	v_mov_b32_e32 v51, v59
	v_mfma_f32_16x16x32_bf16 v[160:163], v[52:55], v[16:19], 0
	v_mfma_f32_16x16x32_bf16 v[164:167], v[52:55], v[20:23], 0
	v_mfma_f32_16x16x32_bf16 v[168:171], v[52:55], v[24:27], 0
	v_mfma_f32_16x16x32_bf16 v[172:175], v[52:55], v[28:31], 0
	v_mfma_f32_16x16x32_bf16 v[176:179], v[52:55], v[32:35], 0
	v_mfma_f32_16x16x32_bf16 v[180:183], v[52:55], v[36:39], 0
	v_mfma_f32_16x16x32_bf16 v[184:187], v[52:55], v[40:43], 0
	v_mfma_f32_16x16x32_bf16 v[188:191], v[52:55], v[44:47], 0
	v_mfma_f32_16x16x32_bf16 v[156:159], v[52:55], v[152:155], 0
	ds_write_b128 v144, v[160:163]
	ds_write_b128 v144, v[164:167] offset:1280
	ds_write_b128 v144, v[168:171] offset:2560
	ds_write_b128 v144, v[172:175] offset:3840
	ds_write_b128 v144, v[176:179] offset:5120
	ds_write_b128 v144, v[180:183] offset:6400
	ds_write_b128 v144, v[184:187] offset:7680
	ds_write_b128 v144, v[188:191] offset:8960
